# m1 + GQA/MLA K/V global-load address arithmetic strength-reduced (scalar row*stride on SALU, per-lane invariant addresses precomputed per unit)
# speedup vs baseline: 1.0005x; 1.0002x over previous
.LBB0_737:
	s_and_b64 vcc, exec, s[4:5]
	s_cbranch_vccz .LBB0_760
	v_mbcnt_lo_u32_b32 v0, -1, 0
	v_mbcnt_hi_u32_b32 v0, -1, v0
	s_add_i32 s4, 0, 0x10000
	v_add_u32_e32 v16, s66, v0
	s_cmp_lg_u32 0, -1
	v_ashrrev_i32_e32 v190, 6, v16
	v_and_b32_e32 v191, 31, v16
	v_and_b32_e32 v0, 0x3fffffc0, v16
	v_lshl_add_u32 v192, v0, 2, s4
	v_lshlrev_b32_e32 v187, 5, v190
	v_or_b32_e32 v0, s86, v191
	v_add_u32_e32 v0, v0, v187
	v_ashrrev_i32_e32 v1, 31, v0
	v_mul_lo_u32 v2, s40, v1
	v_mul_lo_u32 v3, s41, v0
	v_mad_u64_u32 v[0:1], s[4:5], s40, v0, 0
	v_bfe_u32 v189, v16, 5, 1
	v_add3_u32 v1, v1, v2, v3
	v_lshl_add_u64 v[0:1], v[0:1], 1, s[88:89]
	v_lshlrev_b32_e32 v144, 4, v189
	v_ashrrev_i32_e32 v178, 4, v16
	v_lshl_add_u64 v[0:1], v[0:1], 0, v[144:145]
	v_and_b32_e32 v2, 0xfffff0, v178
	v_lshlrev_b32_e32 v3, 1, v178
	global_load_dwordx4 v[124:127], v[0:1], off
	global_load_dwordx4 v[120:123], v[0:1], off offset:32
	global_load_dwordx4 v[116:119], v[0:1], off offset:64
	global_load_dwordx4 v[112:115], v[0:1], off offset:96
	global_load_dwordx4 v[108:111], v[0:1], off offset:128
	global_load_dwordx4 v[104:107], v[0:1], off offset:160
	global_load_dwordx4 v[100:103], v[0:1], off offset:192
	global_load_dwordx4 v[96:99], v[0:1], off offset:224
	v_lshlrev_b32_e32 v0, 3, v16
	v_and_or_b32 v2, v3, 8, v2
	v_and_b32_e32 v1, 0x78, v0
	v_lshrrev_b32_e32 v3, 1, v178
	v_lshrrev_b32_e32 v2, 1, v2
	v_bfe_u32 v0, v0, 5, 2
	v_and_b32_e32 v4, 3, v178
	v_or_b32_e32 v2, v2, v0
	v_and_or_b32 v3, v3, 4, v4
	v_lshlrev_b32_e32 v48, 1, v1
	v_lshlrev_b32_e32 v2, 9, v2
	v_lshlrev_b32_e32 v3, 6, v3
	v_and_b32_e32 v1, 48, v48
	v_add_u32_e32 v18, 32, v178
	v_or3_b32 v17, v2, v3, v1
	v_and_b32_e32 v2, 0xfffff0, v18
	v_lshlrev_b32_e32 v4, 1, v18
	v_and_or_b32 v2, v4, 8, v2
	v_lshrrev_b32_e32 v2, 1, v2
	v_or_b32_e32 v0, v2, v0
	v_and_b32_e32 v186, 63, v16
	v_lshlrev_b32_e32 v0, 9, v0
	v_lshlrev_b32_e32 v188, 4, v16
	v_or3_b32 v19, v0, v3, v1
	v_lshlrev_b32_e32 v0, 3, v186
	v_and_b32_e32 v1, 0xc0, v188
	v_lshlrev_b32_e32 v2, 1, v16
	v_and_or_b32 v1, v0, 24, v1
	v_and_b32_e32 v2, 32, v2
	v_and_b32_e32 v0, 0x100, v0
	s_cselect_b32 s6, 0, 0
	s_ashr_i32 s83, s82, 31
	v_ashrrev_i32_e32 v179, 31, v178
	v_or3_b32 v50, v1, v2, v0
	v_lshl_add_u64 v[0:1], v[178:179], 0, s[82:83]
	v_mul_lo_u32 v2, v1, s40
	v_mul_lo_u32 v3, v0, s41
	v_mad_u64_u32 v[0:1], s[4:5], v0, s40, 0
	v_add3_u32 v1, v1, v3, v2
	v_lshlrev_b64 v[8:9], 1, v[0:1]
	v_lshl_add_u64 v[0:1], s[80:81], 0, v[8:9]
	v_mov_b32_e32 v49, v145
	v_lshl_add_u64 v[0:1], v[0:1], 0, v[48:49]
	v_lshl_add_u64 v[180:181], v[178:179], 0, 32
	global_load_dwordx4 v[0:3], v[0:1], off
	v_lshl_add_u64 v[4:5], v[180:181], 0, s[82:83]
	v_mul_lo_u32 v6, v5, s40
	v_mul_lo_u32 v7, v4, s41
	v_mad_u64_u32 v[4:5], s[4:5], v4, s40, 0
	v_add3_u32 v5, v5, v7, v6
	v_lshlrev_b64 v[12:13], 1, v[4:5]
	v_lshl_add_u64 v[4:5], s[80:81], 0, v[12:13]
	v_lshl_add_u64 v[8:9], s[78:79], 0, v[8:9]
	v_lshl_add_u64 v[12:13], s[78:79], 0, v[12:13]
	v_lshl_add_u64 v[4:5], v[4:5], 0, v[48:49]
	v_lshl_add_u64 v[8:9], v[8:9], 0, v[48:49]
	v_lshl_add_u64 v[12:13], v[12:13], 0, v[48:49]
	global_load_dwordx4 v[4:7], v[4:5], off
	v_add_u32_e32 v195, 0, v17
	global_load_dwordx4 v[8:11], v[8:9], off
	v_lshlrev_b32_e32 v51, 8, v191
	global_load_dwordx4 v[12:15], v[12:13], off
	s_waitcnt vmcnt(0)
	v_and_b32_e32 v60, 0x70, v188
	v_add_u32_e32 v196, 0, v19
	v_or_b32_e32 v52, 32, v144
	v_bitop3_b32 v52, v52, v51, v60 bitop3:0xde
	v_add_u32_e32 v208, 0, v52
	v_readlane_b32 s16, v253, 56
	v_readlane_b32 s17, v253, 57
	v_readlane_b32 s18, v253, 58
	v_readlane_b32 s19, v253, 59
	s_mov_b32 s14, 4
	v_readlane_b32 s20, v253, 60
	v_readlane_b32 s21, v253, 61
	v_readlane_b32 s22, v253, 62
	v_readlane_b32 s23, v253, 63
	v_readlane_b32 s24, v254, 0
	v_readlane_b32 s25, v254, 1
	v_readlane_b32 s26, v254, 2
	v_readlane_b32 s27, v254, 3
	v_readlane_b32 s28, v254, 4
	v_readlane_b32 s29, v254, 5
	v_readlane_b32 s30, v254, 6
	v_readlane_b32 s31, v254, 7
	s_mov_b32 s17, s16
	s_mov_b32 s18, s16
	s_mov_b32 s19, s16
	s_mov_b32 s4, s16
	v_add_u32_e32 v193, s6, v50
	s_mov_b32 s20, s16
	s_mov_b32 s21, s16
	s_mov_b32 s22, s16
	s_mov_b32 s23, s16
	s_mov_b32 s24, s16
	s_mov_b32 s25, s16
	s_mov_b32 s26, s16
	s_mov_b32 s27, s16
	s_mov_b32 s28, s16
	s_mov_b32 s29, s16
	s_mov_b32 s30, s16
	s_mov_b32 s31, s16
	v_writelane_b32 v253, s4, 56
	v_lshl_add_u64 v[182:183], s[80:81], 0, v[48:49]
	v_lshl_add_u64 v[184:185], s[78:79], 0, v[48:49]
	v_writelane_b32 v254, s12, 0
	v_writelane_b32 v254, s13, 1
	v_writelane_b32 v254, s14, 2
	v_writelane_b32 v254, s15, 3
	v_writelane_b32 v254, s16, 4
	v_writelane_b32 v254, s17, 5
	v_writelane_b32 v254, s18, 6
	v_writelane_b32 v254, s19, 7
	v_writelane_b32 v253, s5, 57
	v_writelane_b32 v253, s6, 58
	v_writelane_b32 v253, s7, 59
	v_writelane_b32 v253, s8, 60
	v_writelane_b32 v253, s9, 61
	v_writelane_b32 v253, s10, 62
	v_writelane_b32 v253, s11, 63
	v_lshl_add_u32 v194, v191, 2, v192
	v_mov_b32_e32 v203, 0
	s_waitcnt vmcnt(0)
	ds_write_b128 v195, v[0:3]
	v_lshlrev_b32_e32 v0, 8, v178
	v_and_b32_e32 v1, 0x70, v16
	v_bitop3_b32 v0, v48, v0, v1 bitop3:0xde
	v_add_u32_e32 v198, 0, v0
	v_lshlrev_b32_e32 v0, 8, v18
	v_bitop3_b32 v0, v48, v0, v1 bitop3:0xde
	v_add_u32_e32 v199, 0, v0
	v_bitop3_b32 v0, v144, v51, v60 bitop3:0xde
	v_add_u32_e32 v200, 0, v0
	ds_write_b128 v196, v[4:7]
	ds_write_b128 v198, v[8:11] offset:32768
	ds_write_b128 v199, v[12:15] offset:32768
	s_waitcnt lgkmcnt(0)
	s_barrier
	ds_read_b128 v[16:19], v200 offset:32768
	ds_read_b128 v[20:23], v200 offset:40960
	s_waitcnt lgkmcnt(1)
	v_mfma_f32_32x32x16_bf16 v[32:47], v[16:19], v[124:127], 0
	ds_read_b128 v[52:55], v208 offset:32768
	ds_read_b128 v[56:59], v208 offset:40960
	v_mov_b64_e32 v[0:1], s[16:17]
	v_mov_b64_e32 v[14:15], s[30:31]
	v_mov_b64_e32 v[2:3], s[18:19]
	v_mov_b64_e32 v[4:5], s[20:21]
	v_mov_b64_e32 v[6:7], s[22:23]
	v_mov_b64_e32 v[8:9], s[24:25]
	s_waitcnt lgkmcnt(2)
	v_mfma_f32_32x32x16_bf16 v[16:31], v[20:23], v[124:127], 0
	v_mov_b64_e32 v[10:11], s[26:27]
	v_mov_b64_e32 v[12:13], s[28:29]
	s_waitcnt lgkmcnt(1)
	v_mfma_f32_32x32x16_bf16 v[32:47], v[52:55], v[120:123], v[32:47]
	v_or_b32_e32 v52, 64, v144
	v_bitop3_b32 v52, v52, v51, v60 bitop3:0xde
	v_add_u32_e32 v207, 0, v52
	s_waitcnt lgkmcnt(0)
	v_mfma_f32_32x32x16_bf16 v[16:31], v[56:59], v[120:123], v[16:31]
	ds_read_b128 v[52:55], v207 offset:32768
	ds_read_b128 v[56:59], v207 offset:40960
	s_waitcnt lgkmcnt(1)
	v_mfma_f32_32x32x16_bf16 v[32:47], v[52:55], v[116:119], v[32:47]
	v_or_b32_e32 v52, 0x60, v144
	v_bitop3_b32 v52, v52, v51, v60 bitop3:0xde
	v_add_u32_e32 v206, 0, v52
	s_waitcnt lgkmcnt(0)
	v_mfma_f32_32x32x16_bf16 v[16:31], v[56:59], v[116:119], v[16:31]
	ds_read_b128 v[52:55], v206 offset:32768
	ds_read_b128 v[56:59], v206 offset:40960
	s_waitcnt lgkmcnt(1)
	v_mfma_f32_32x32x16_bf16 v[32:47], v[52:55], v[112:115], v[32:47]
	v_or_b32_e32 v52, 0x80, v144
	v_bitop3_b32 v52, v52, v51, v60 bitop3:0xde
	v_add_u32_e32 v205, 0, v52
	s_waitcnt lgkmcnt(0)
	v_mfma_f32_32x32x16_bf16 v[16:31], v[56:59], v[112:115], v[16:31]
	ds_read_b128 v[52:55], v205 offset:32768
	ds_read_b128 v[56:59], v205 offset:40960
	s_waitcnt lgkmcnt(1)
	v_mfma_f32_32x32x16_bf16 v[32:47], v[52:55], v[108:111], v[32:47]
	v_or_b32_e32 v52, 0xa0, v144
	v_bitop3_b32 v52, v52, v51, v60 bitop3:0xde
	v_add_u32_e32 v204, 0, v52
	s_waitcnt lgkmcnt(0)
	v_mfma_f32_32x32x16_bf16 v[16:31], v[56:59], v[108:111], v[16:31]
	ds_read_b128 v[52:55], v204 offset:32768
	ds_read_b128 v[56:59], v204 offset:40960
	s_waitcnt lgkmcnt(1)
	v_mfma_f32_32x32x16_bf16 v[32:47], v[52:55], v[104:107], v[32:47]
	v_or_b32_e32 v52, 0xc0, v144
	v_bitop3_b32 v52, v52, v51, v60 bitop3:0xde
	v_add_u32_e32 v202, 0, v52
	s_waitcnt lgkmcnt(0)
	v_mfma_f32_32x32x16_bf16 v[16:31], v[56:59], v[104:107], v[16:31]
	ds_read_b128 v[52:55], v202 offset:32768
	ds_read_b128 v[56:59], v202 offset:40960
	s_waitcnt lgkmcnt(1)
	v_mfma_f32_32x32x16_bf16 v[32:47], v[52:55], v[100:103], v[32:47]
	v_or_b32_e32 v52, 0xe0, v144
	v_bitop3_b32 v51, v52, v51, v60 bitop3:0xde
	v_add_u32_e32 v201, 0, v51
	s_waitcnt lgkmcnt(0)
	v_mfma_f32_32x32x16_bf16 v[16:31], v[56:59], v[100:103], v[16:31]
	ds_read_b128 v[52:55], v201 offset:32768
	ds_read_b128 v[56:59], v201 offset:40960
	s_waitcnt lgkmcnt(1)
	v_mfma_f32_32x32x16_bf16 v[32:47], v[52:55], v[96:99], v[32:47]
	s_waitcnt lgkmcnt(0)
	v_mfma_f32_32x32x16_bf16 v[16:31], v[56:59], v[96:99], v[16:31]
	s_nop 9
	v_max_f32_e32 v51, v33, v33
	v_max_f32_e32 v52, v32, v32
	v_max_f32_e32 v51, v52, v51
	v_max3_f32 v51, v51, v34, v35
	v_max3_f32 v51, v51, v36, v37
	v_max3_f32 v51, v51, v38, v39
	v_max3_f32 v51, v51, v40, v41
	v_max3_f32 v51, v51, v42, v43
	v_max3_f32 v51, v51, v44, v45
	v_max3_f32 v51, v51, v46, v47
	v_max3_f32 v51, v51, v16, v17
	v_max3_f32 v51, v51, v18, v19
	v_max3_f32 v51, v51, v20, v21
	v_max3_f32 v51, v51, v22, v23
	v_max3_f32 v51, v51, v24, v25
	v_max3_f32 v51, v51, v26, v27
	v_max3_f32 v51, v51, v28, v29
	v_max3_f32 v51, v51, v30, v31
	v_mov_b32_e32 v52, v51
	s_nop 1
	v_permlane32_swap_b32_e32 v51, v52
	v_max_f32_e32 v52, v52, v52
	v_max_f32_e32 v51, v51, v51
	v_max_f32_e32 v51, v51, v52
	v_add_f32_e32 v52, 0x7149f2ca, v51
	v_max_f32_e32 v51, 0xf149f2ca, v51
	v_cmp_ge_f32_e32 vcc, s93, v52
	v_sub_f32_e32 v52, 0xf149f2ca, v51
	v_mul_f32_e32 v52, 0x3e0293ee, v52
	v_exp_f32_e32 v52, v52
	s_cmp_eq_u64 vcc, exec
	s_cselect_b64 vcc, -1, 0
	v_cndmask_b32_e32 v174, v51, v231, vcc
	s_add_i32 s4, s46, 0x4040
	v_cndmask_b32_e64 v209, v52, 1.0, vcc
	v_mul_f32_e32 v52, 0xbe0293ee, v174
	s_ashr_i32 s5, s4, 31
	v_fma_f32 v150, v20, s92, v52
	v_fma_f32 v151, v21, s92, v52
	v_lshl_add_u64 v[20:21], v[180:181], 0, s[4:5]
	v_fma_f32 v148, v22, s92, v52
	v_fma_f32 v149, v23, s92, v52
	v_fma_f32 v158, v16, s92, v52
	v_fma_f32 v159, v17, s92, v52
	v_lshl_add_u64 v[16:17], v[178:179], 0, s[4:5]
	v_mul_lo_u32 v22, v21, s40
	v_mul_lo_u32 v23, v20, s41
	v_mad_u64_u32 v[20:21], s[4:5], v20, s40, 0
	s_add_i32 s4, s46, 0x4080
	v_fmamk_f32 v32, v32, 0x3e0293ee, v52
	v_fmamk_f32 v33, v33, 0x3e0293ee, v52
	s_ashr_i32 s5, s4, 31
	v_fmamk_f32 v34, v34, 0x3e0293ee, v52
	v_fmamk_f32 v35, v35, 0x3e0293ee, v52
	v_exp_f32_e32 v162, v32
	v_exp_f32_e32 v216, v33
	v_lshl_add_u64 v[32:33], v[178:179], 0, s[4:5]
	v_exp_f32_e32 v163, v34
	v_exp_f32_e32 v177, v35
	v_mul_lo_u32 v34, v33, s40
	v_mul_lo_u32 v35, v32, s41
	v_mad_u64_u32 v[32:33], s[8:9], v32, s40, 0
	v_add3_u32 v33, v33, v35, v34
	v_lshlrev_b64 v[32:33], 1, v[32:33]
	v_lshl_add_u64 v[34:35], s[80:81], 0, v[32:33]
	v_fma_f32 v156, v18, s92, v52
	v_fma_f32 v157, v19, s92, v52
	v_mul_lo_u32 v18, v17, s40
	v_mul_lo_u32 v19, v16, s41
	v_mad_u64_u32 v[16:17], s[8:9], v16, s40, 0
	v_lshl_add_u64 v[34:35], v[34:35], 0, v[48:49]
	v_fmamk_f32 v36, v36, 0x3e0293ee, v52
	v_fmamk_f32 v37, v37, 0x3e0293ee, v52
	v_add3_u32 v17, v17, v19, v18
	global_load_dwordx4 v[128:131], v[34:35], off
	v_lshl_add_u64 v[34:35], v[180:181], 0, s[4:5]
	v_fma_f32 v146, v24, s92, v52
	v_fma_f32 v147, v25, s92, v52
	v_exp_f32_e32 v164, v36
	v_exp_f32_e32 v176, v37
	v_lshlrev_b64 v[24:25], 1, v[16:17]
	v_add3_u32 v21, v21, v23, v22
	v_mul_lo_u32 v36, v35, s40
	v_mul_lo_u32 v37, v34, s41
	v_mad_u64_u32 v[34:35], s[4:5], v34, s40, 0
	v_fma_f32 v154, v28, s92, v52
	v_fma_f32 v155, v29, s92, v52
	v_lshl_add_u64 v[16:17], s[80:81], 0, v[24:25]
	v_lshlrev_b64 v[28:29], 1, v[20:21]
	v_add3_u32 v35, v35, v37, v36
	v_lshl_add_u64 v[32:33], s[78:79], 0, v[32:33]
	v_lshl_add_u64 v[16:17], v[16:17], 0, v[48:49]
	v_lshl_add_u64 v[20:21], s[80:81], 0, v[28:29]
	v_lshlrev_b64 v[34:35], 1, v[34:35]
	v_lshl_add_u64 v[32:33], v[32:33], 0, v[48:49]
	global_load_dwordx4 v[16:19], v[16:17], off
	v_lshl_add_u64 v[20:21], v[20:21], 0, v[48:49]
	v_lshl_add_u64 v[24:25], s[78:79], 0, v[24:25]
	v_lshl_add_u64 v[36:37], s[80:81], 0, v[34:35]
	global_load_dwordx4 v[136:139], v[32:33], off
	v_lshl_add_u64 v[32:33], s[78:79], 0, v[34:35]
	global_load_dwordx4 v[20:23], v[20:21], off
	v_lshl_add_u64 v[24:25], v[24:25], 0, v[48:49]
	v_lshl_add_u64 v[28:29], s[78:79], 0, v[28:29]
	v_lshl_add_u64 v[36:37], v[36:37], 0, v[48:49]
	v_lshl_add_u64 v[32:33], v[32:33], 0, v[48:49]
	v_fma_f32 v160, v26, s92, v52
	v_fma_f32 v161, v27, s92, v52
	global_load_dwordx4 v[24:27], v[24:25], off
	v_lshl_add_u64 v[28:29], v[28:29], 0, v[48:49]
	global_load_dwordx4 v[132:135], v[36:37], off
	global_load_dwordx4 v[140:143], v[32:33], off
	v_fma_f32 v152, v30, s92, v52
	v_fma_f32 v153, v31, s92, v52
	global_load_dwordx4 v[28:31], v[28:29], off
	v_mov_b32_e32 v51, v52
	v_fmamk_f32 v38, v38, 0x3e0293ee, v52
	v_fmamk_f32 v39, v39, 0x3e0293ee, v52
	v_fmamk_f32 v40, v40, 0x3e0293ee, v52
	v_fmamk_f32 v41, v41, 0x3e0293ee, v52
	v_fmamk_f32 v42, v42, 0x3e0293ee, v52
	v_fmamk_f32 v43, v43, 0x3e0293ee, v52
	v_fmamk_f32 v44, v44, 0x3e0293ee, v52
	v_fmamk_f32 v45, v45, 0x3e0293ee, v52
	v_fmamk_f32 v46, v46, 0x3e0293ee, v52
	v_fmac_f32_e32 v51, 0x3e0293ee, v47
	v_exp_f32_e32 v165, v38
	v_exp_f32_e32 v175, v39
	v_exp_f32_e32 v166, v40
	v_exp_f32_e32 v173, v41
	v_exp_f32_e32 v167, v42
	v_exp_f32_e32 v172, v43
	v_exp_f32_e32 v168, v44
	v_exp_f32_e32 v171, v45
	v_exp_f32_e32 v169, v46
	v_exp_f32_e32 v170, v51
	s_waitcnt vmcnt(4)
	s_addk_i32 s6, 0x4000
	s_waitcnt vmcnt(6)
	ds_write_b128 v195, v[16:19] offset:16384
	s_waitcnt vmcnt(4)
	ds_write_b128 v196, v[20:23] offset:16384
	s_waitcnt vmcnt(3)
	ds_write_b128 v198, v[24:27] offset:49152
	s_waitcnt vmcnt(0)
	ds_write_b128 v199, v[28:31] offset:49152
	v_add_u32_e32 v197, s6, v50
	v_mov_b64_e32 v[30:31], v[14:15]
	v_mov_b64_e32 v[46:47], v[14:15]
	v_mov_b64_e32 v[62:63], v[14:15]
	v_cmp_gt_u32_e64 s[4:5], 32, v186
	s_add_i32 s15, s46, 0x40c0
	s_mov_b32 s8, s68
	v_mov_b64_e32 v[28:29], v[12:13]
	v_mov_b64_e32 v[26:27], v[10:11]
	v_mov_b64_e32 v[24:25], v[8:9]
	v_mov_b64_e32 v[22:23], v[6:7]
	v_mov_b64_e32 v[20:21], v[4:5]
	v_mov_b64_e32 v[18:19], v[2:3]
	v_mov_b64_e32 v[16:17], v[0:1]
	v_mov_b64_e32 v[44:45], v[12:13]
	v_mov_b64_e32 v[42:43], v[10:11]
	v_mov_b64_e32 v[40:41], v[8:9]
	v_mov_b64_e32 v[38:39], v[6:7]
	v_mov_b64_e32 v[36:37], v[4:5]
	v_mov_b64_e32 v[34:35], v[2:3]
	v_mov_b64_e32 v[32:33], v[0:1]
	v_mov_b64_e32 v[60:61], v[12:13]
	v_mov_b64_e32 v[58:59], v[10:11]
	v_mov_b64_e32 v[56:57], v[8:9]
	v_mov_b64_e32 v[54:55], v[6:7]
	v_mov_b64_e32 v[52:53], v[4:5]
	v_mov_b64_e32 v[50:51], v[2:3]
	v_mov_b64_e32 v[48:49], v[0:1]
	v_mul_lo_u32 v232, v179, s40
	v_mul_lo_u32 v233, v178, s41
	v_mad_u64_u32 v[234:235], s[100:101], v178, s40, 0
	v_add3_u32 v235, v235, v233, v232
	v_lshlrev_b64 v[234:235], 1, v[234:235]
	v_mul_lo_u32 v232, v181, s40
	v_mul_lo_u32 v233, v180, s41
	v_mad_u64_u32 v[236:237], s[100:101], v180, s40, 0
	v_add3_u32 v237, v237, v233, v232
	v_lshlrev_b64 v[236:237], 1, v[236:237]
	v_lshl_add_u64 v[178:179], v[182:183], 0, v[234:235]
	v_lshl_add_u64 v[180:181], v[182:183], 0, v[236:237]
	v_lshl_add_u64 v[182:183], v[184:185], 0, v[234:235]
	v_lshl_add_u64 v[184:185], v[184:185], 0, v[236:237]
	s_waitcnt lgkmcnt(0)
	s_barrier
.LBB0_739:
	ds_read_b128 v[236:239], v200 offset:49152
	ds_read_b128 v[240:243], v208 offset:49152
	ds_read_b128 v[244:247], v207 offset:49152
	ds_read_b128 v[248:251], v206 offset:49152
	s_add_i32 s6, s14, -3
	s_waitcnt lgkmcnt(3)
	v_mfma_f32_32x32x16_bf16 v[80:95], v[236:239], v[124:127], 0
	ds_read_b128 v[236:239], v205 offset:49152
	v_exp_f32_e32 v158, v158
	v_exp_f32_e32 v159, v159
	v_add_f32_e32 v210, 0, v162
	s_waitcnt lgkmcnt(3)
	v_mfma_f32_32x32x16_bf16 v[80:95], v[240:243], v[120:123], v[80:95]
	ds_read_b128 v[240:243], v204 offset:49152
	v_exp_f32_e32 v156, v156
	v_exp_f32_e32 v157, v157
	v_add_f32_e32 v210, v216, v210
	s_waitcnt lgkmcnt(3)
	v_mfma_f32_32x32x16_bf16 v[80:95], v[244:247], v[116:119], v[80:95]
	ds_read_b128 v[244:247], v202 offset:49152
	v_exp_f32_e32 v150, v150
	v_exp_f32_e32 v151, v151
	v_add_f32_e32 v210, v163, v210
	s_waitcnt lgkmcnt(3)
	v_mfma_f32_32x32x16_bf16 v[80:95], v[248:251], v[112:115], v[80:95]
	ds_read_b128 v[248:251], v201 offset:49152
	v_exp_f32_e32 v148, v148
	v_exp_f32_e32 v149, v149
	v_add_f32_e32 v210, v177, v210
	s_waitcnt lgkmcnt(3)
	v_mfma_f32_32x32x16_bf16 v[80:95], v[236:239], v[108:111], v[80:95]
	ds_read_b128 v[236:239], v200 offset:57344
	v_exp_f32_e32 v146, v146
	v_exp_f32_e32 v147, v147
	v_add_f32_e32 v210, v164, v210
	s_waitcnt lgkmcnt(3)
	v_mfma_f32_32x32x16_bf16 v[80:95], v[240:243], v[104:107], v[80:95]
	ds_read_b128 v[240:243], v208 offset:57344
	v_exp_f32_e32 v160, v160
	v_exp_f32_e32 v161, v161
	v_add_f32_e32 v210, v176, v210
	s_waitcnt lgkmcnt(3)
	v_mfma_f32_32x32x16_bf16 v[80:95], v[244:247], v[100:103], v[80:95]
	ds_read_b128 v[244:247], v207 offset:57344
	v_exp_f32_e32 v154, v154
	v_exp_f32_e32 v155, v155
	v_add_f32_e32 v210, v165, v210
	s_waitcnt lgkmcnt(3)
	v_mfma_f32_32x32x16_bf16 v[80:95], v[248:251], v[96:99], v[80:95]
	ds_read_b128 v[248:251], v206 offset:57344
	v_exp_f32_e32 v152, v152
	v_exp_f32_e32 v153, v153
	v_add_f32_e32 v210, v175, v210
	s_waitcnt lgkmcnt(3)
	v_mfma_f32_32x32x16_bf16 v[64:79], v[236:239], v[124:127], 0
	ds_read_b128 v[236:239], v205 offset:57344
	v_add_f32_e32 v210, v166, v210
	v_add_f32_e32 v210, v173, v210
	v_add_f32_e32 v210, v167, v210
	v_add_f32_e32 v210, v172, v210
	v_add_f32_e32 v210, v168, v210
	s_waitcnt lgkmcnt(3)
	v_mfma_f32_32x32x16_bf16 v[64:79], v[240:243], v[120:123], v[64:79]
	ds_read_b128 v[240:243], v204 offset:57344
	v_add_f32_e32 v210, v171, v210
	v_add_f32_e32 v210, v169, v210
	v_add_f32_e32 v210, v170, v210
	v_add_f32_e32 v210, v158, v210
	v_add_f32_e32 v210, v159, v210
	s_waitcnt lgkmcnt(3)
	v_mfma_f32_32x32x16_bf16 v[64:79], v[244:247], v[116:119], v[64:79]
	ds_read_b128 v[244:247], v202 offset:57344
	v_add_f32_e32 v210, v156, v210
	v_add_f32_e32 v210, v157, v210
	v_add_f32_e32 v210, v150, v210
	v_add_f32_e32 v210, v151, v210
	v_add_f32_e32 v210, v148, v210
	s_waitcnt lgkmcnt(3)
	v_mfma_f32_32x32x16_bf16 v[64:79], v[248:251], v[112:115], v[64:79]
	ds_read_b128 v[248:251], v201 offset:57344
	v_add_f32_e32 v210, v149, v210
	v_add_f32_e32 v210, v146, v210
	v_add_f32_e32 v210, v147, v210
	v_add_f32_e32 v210, v160, v210
	v_add_f32_e32 v210, v161, v210
	s_waitcnt lgkmcnt(3)
	v_mfma_f32_32x32x16_bf16 v[64:79], v[236:239], v[108:111], v[64:79]
	v_add_f32_e32 v210, v154, v210
	v_add_f32_e32 v210, v155, v210
	v_add_f32_e32 v210, v152, v210
	v_add_f32_e32 v210, v153, v210
	v_mov_b32_e32 v211, v210
	s_waitcnt lgkmcnt(2)
	v_mfma_f32_32x32x16_bf16 v[64:79], v[240:243], v[104:107], v[64:79]
	v_cvt_pk_bf16_f32 v162, v162, v216
	v_cvt_pk_bf16_f32 v163, v163, v177
	v_cvt_pk_bf16_f32 v164, v164, v176
	v_permlane32_swap_b32_e32 v210, v211
	v_cvt_pk_bf16_f32 v165, v165, v175
	ds_read_b64_tr_b16 v[216:217], v193 offset:0
	ds_read_b64_tr_b16 v[218:219], v193 offset:0x800
	ds_read_b64_tr_b16 v[220:221], v193 offset:0x1000
	ds_read_b64_tr_b16 v[222:223], v193 offset:0x1800
	ds_read_b64_tr_b16 v[224:225], v193 offset:0x2000
	ds_read_b64_tr_b16 v[226:227], v193 offset:0x2800
	ds_read_b64_tr_b16 v[232:233], v193 offset:0x3000
	ds_read_b64_tr_b16 v[234:235], v193 offset:0x3800
	s_waitcnt lgkmcnt(9)
	v_mfma_f32_32x32x16_bf16 v[64:79], v[244:247], v[100:103], v[64:79]
	v_permlane32_swap_b32_e32 v162, v164
	v_cvt_pk_bf16_f32 v166, v166, v173
	v_cvt_pk_bf16_f32 v167, v167, v172
	v_cvt_pk_bf16_f32 v168, v168, v171
	v_cvt_pk_bf16_f32 v169, v169, v170
	s_waitcnt lgkmcnt(8)
	v_mfma_f32_32x32x16_bf16 v[64:79], v[248:251], v[96:99], v[64:79]
	v_cvt_pk_bf16_f32 v170, v158, v159
	v_cvt_pk_bf16_f32 v171, v156, v157
	v_cvt_pk_bf16_f32 v172, v150, v151
	v_cvt_pk_bf16_f32 v173, v148, v149
	v_cvt_pk_bf16_f32 v212, v146, v147
	s_waitcnt vmcnt(0)
	ds_write_b128 v198, v[136:139] offset:32768
	ds_write_b128 v199, v[140:143] offset:32768
	s_sub_i32 s7, s8, 64
	s_cmp_lt_u32 s6, 2
	s_cselect_b32 s6, s15, s7
	s_ashr_i32 s7, s6, 31
	s_mul_hi_u32 s100, s6, s40
	s_mul_i32 s101, s6, s41
	s_add_u32 s100, s100, s101
	s_mul_i32 s101, s7, s40
	s_add_u32 s100, s100, s101
	s_mul_i32 s6, s6, s40
	s_mov_b32 s7, s100
	s_lshl_b64 s[6:7], s[6:7], 1
	v_permlane32_swap_b32_e32 v163, v165
	s_waitcnt lgkmcnt(8)
	s_nop 0
	v_mfma_f32_32x32x16_bf16 v[48:63], v[162:165], v[216:219], v[48:63]
	ds_read_b64_tr_b16 v[216:217], v193 offset:0x200
	ds_read_b64_tr_b16 v[218:219], v193 offset:0xa00
	v_cvt_pk_bf16_f32 v213, v160, v161
	v_cvt_pk_bf16_f32 v214, v154, v155
	v_cvt_pk_bf16_f32 v215, v152, v153
	v_permlane32_swap_b32_e32 v166, v168
	v_permlane32_swap_b32_e32 v167, v169
	s_waitcnt lgkmcnt(8)
	s_nop 0
	v_mfma_f32_32x32x16_bf16 v[48:63], v[166:169], v[220:223], v[48:63]
	ds_read_b64_tr_b16 v[220:221], v193 offset:0x1200
	ds_read_b64_tr_b16 v[222:223], v193 offset:0x1a00
	v_permlane32_swap_b32_e32 v170, v172
	v_permlane32_swap_b32_e32 v171, v173
	v_permlane32_swap_b32_e32 v212, v214
	v_permlane32_swap_b32_e32 v213, v215
	v_lshl_add_u64 v[146:147], s[6:7], 0, v[178:179]
	s_waitcnt lgkmcnt(8)
	v_mfma_f32_32x32x16_bf16 v[48:63], v[170:173], v[224:227], v[48:63]
	ds_read_b64_tr_b16 v[224:225], v193 offset:0x2200
	ds_read_b64_tr_b16 v[226:227], v193 offset:0x2a00
	v_lshl_add_u64 v[150:151], s[6:7], 0, v[180:181]
	v_lshl_add_u64 v[154:155], s[6:7], 0, v[182:183]
	v_lshl_add_u64 v[158:159], s[6:7], 0, v[184:185]
	v_max_f32_e32 v250, v81, v81
	v_max_f32_e32 v251, v80, v80
	s_waitcnt lgkmcnt(8)
	v_mfma_f32_32x32x16_bf16 v[48:63], v[212:215], v[232:235], v[48:63]
	ds_read_b64_tr_b16 v[232:233], v193 offset:0x3200
	ds_read_b64_tr_b16 v[234:235], v193 offset:0x3a00
	v_max_f32_e32 v250, v251, v250
	v_max3_f32 v250, v250, v82, v83
	v_max3_f32 v250, v250, v84, v85
	v_max3_f32 v250, v250, v86, v87
	v_max3_f32 v250, v250, v88, v89
	s_waitcnt lgkmcnt(6)
	v_mfma_f32_32x32x16_bf16 v[32:47], v[162:165], v[216:219], v[32:47]
	ds_read_b64_tr_b16 v[216:217], v193 offset:0x400
	ds_read_b64_tr_b16 v[218:219], v193 offset:0xc00
	v_max3_f32 v250, v250, v90, v91
	v_max3_f32 v250, v250, v92, v93
	v_max3_f32 v250, v250, v94, v95
	v_max3_f32 v250, v250, v64, v65
	v_max3_f32 v250, v250, v66, v67
	s_waitcnt lgkmcnt(6)
	v_mfma_f32_32x32x16_bf16 v[32:47], v[166:169], v[220:223], v[32:47]
	ds_read_b64_tr_b16 v[220:221], v193 offset:0x1400
	ds_read_b64_tr_b16 v[222:223], v193 offset:0x1c00
	v_max3_f32 v250, v250, v68, v69
	v_max3_f32 v250, v250, v70, v71
	v_max3_f32 v250, v250, v72, v73
	v_max3_f32 v250, v250, v74, v75
	v_max3_f32 v250, v250, v76, v77
	global_load_dwordx4 v[146:149], v[146:147], off
	global_load_dwordx4 v[150:153], v[150:151], off
	global_load_dwordx4 v[154:157], v[154:155], off
	global_load_dwordx4 v[158:161], v[158:159], off
	s_waitcnt lgkmcnt(6)
	v_mfma_f32_32x32x16_bf16 v[32:47], v[170:173], v[224:227], v[32:47]
	ds_read_b64_tr_b16 v[224:225], v193 offset:0x2400
	ds_read_b64_tr_b16 v[226:227], v193 offset:0x2c00
	v_max3_f32 v250, v250, v78, v79
	v_mov_b32_e32 v251, v250
	s_nop 1
	v_permlane32_swap_b32_e32 v250, v251
	v_max_f32_e32 v251, v251, v251
	v_max_f32_e32 v250, v250, v250
	s_waitcnt lgkmcnt(6)
	v_mfma_f32_32x32x16_bf16 v[32:47], v[212:215], v[232:235], v[32:47]
	ds_read_b64_tr_b16 v[232:233], v193 offset:0x3400
	ds_read_b64_tr_b16 v[234:235], v193 offset:0x3c00
	v_max_f32_e32 v250, v250, v251
	v_sub_f32_e32 v251, v250, v174
	v_cmp_ge_f32_e32 vcc, s93, v251
	v_max_f32_e32 v251, v174, v174
	v_max_f32_e32 v250, v251, v250
	s_waitcnt lgkmcnt(6)
	v_mfma_f32_32x32x16_bf16 v[16:31], v[162:165], v[216:219], v[16:31]
	ds_read_b64_tr_b16 v[216:217], v193 offset:0x600
	ds_read_b64_tr_b16 v[218:219], v193 offset:0xe00
	v_sub_f32_e32 v251, v174, v250
	v_mul_f32_e32 v251, 0x3e0293ee, v251
	v_exp_f32_e32 v251, v251
	s_waitcnt lgkmcnt(6)
	v_mfma_f32_32x32x16_bf16 v[16:31], v[166:169], v[220:223], v[16:31]
	ds_read_b64_tr_b16 v[220:221], v193 offset:0x1600
	ds_read_b64_tr_b16 v[222:223], v193 offset:0x1e00
	s_waitcnt lgkmcnt(6)
	v_mfma_f32_32x32x16_bf16 v[16:31], v[170:173], v[224:227], v[16:31]
	ds_read_b64_tr_b16 v[224:225], v193 offset:0x2600
	ds_read_b64_tr_b16 v[226:227], v193 offset:0x2e00
	s_waitcnt lgkmcnt(6)
	v_mfma_f32_32x32x16_bf16 v[16:31], v[212:215], v[232:235], v[16:31]
	ds_read_b64_tr_b16 v[232:233], v193 offset:0x3600
	ds_read_b64_tr_b16 v[234:235], v193 offset:0x3e00
	s_waitcnt lgkmcnt(6)
	v_mfma_f32_32x32x16_bf16 v[0:15], v[162:165], v[216:219], v[0:15]
	s_waitcnt lgkmcnt(4)
	v_mfma_f32_32x32x16_bf16 v[0:15], v[166:169], v[220:223], v[0:15]
	s_waitcnt lgkmcnt(2)
	v_mfma_f32_32x32x16_bf16 v[0:15], v[170:173], v[224:227], v[0:15]
	s_waitcnt lgkmcnt(0)
	v_mfma_f32_32x32x16_bf16 v[0:15], v[212:215], v[232:235], v[0:15]
	s_cmp_eq_u64 vcc, exec
	s_cselect_b64 s[6:7], -1, 0
	s_branch .Lgqa_joinA
.Lgqa_loopA:
	ds_read_b128 v[236:239], v200 offset:49152
	ds_read_b128 v[240:243], v208 offset:49152
	ds_read_b128 v[244:247], v207 offset:49152
	ds_read_b128 v[248:251], v206 offset:49152
	s_add_i32 s6, s14, -3
	s_waitcnt lgkmcnt(3)
	v_mfma_f32_32x32x16_bf16 v[80:95], v[236:239], v[124:127], 0
	ds_read_b128 v[236:239], v205 offset:49152
	v_exp_f32_e32 v162, v162
	v_exp_f32_e32 v216, v216
	v_fma_f32 v158, v64, s92, v152
	v_fma_f32 v159, v65, s92, v152
	s_waitcnt lgkmcnt(3)
	v_mfma_f32_32x32x16_bf16 v[80:95], v[240:243], v[120:123], v[80:95]
	ds_read_b128 v[240:243], v204 offset:49152
	v_exp_f32_e32 v163, v163
	v_exp_f32_e32 v177, v177
	v_fma_f32 v156, v66, s92, v152
	v_fma_f32 v157, v67, s92, v152
	s_waitcnt lgkmcnt(3)
	v_mfma_f32_32x32x16_bf16 v[80:95], v[244:247], v[116:119], v[80:95]
	ds_read_b128 v[244:247], v202 offset:49152
	v_exp_f32_e32 v164, v164
	v_exp_f32_e32 v176, v176
	v_fma_f32 v150, v68, s92, v152
	v_fma_f32 v151, v69, s92, v152
	s_waitcnt lgkmcnt(3)
	v_mfma_f32_32x32x16_bf16 v[80:95], v[248:251], v[112:115], v[80:95]
	ds_read_b128 v[248:251], v201 offset:49152
	v_exp_f32_e32 v165, v165
	v_exp_f32_e32 v175, v175
	v_fma_f32 v148, v70, s92, v152
	v_fma_f32 v149, v71, s92, v152
	s_waitcnt lgkmcnt(3)
	v_mfma_f32_32x32x16_bf16 v[80:95], v[236:239], v[108:111], v[80:95]
	ds_read_b128 v[236:239], v200 offset:57344
	v_exp_f32_e32 v166, v166
	v_exp_f32_e32 v173, v173
	v_fma_f32 v146, v72, s92, v152
	v_fma_f32 v147, v73, s92, v152
	s_waitcnt lgkmcnt(3)
	v_mfma_f32_32x32x16_bf16 v[80:95], v[240:243], v[104:107], v[80:95]
	ds_read_b128 v[240:243], v208 offset:57344
	v_exp_f32_e32 v167, v167
	v_exp_f32_e32 v172, v172
	v_fma_f32 v160, v74, s92, v152
	v_fma_f32 v161, v75, s92, v152
	s_waitcnt lgkmcnt(3)
	v_mfma_f32_32x32x16_bf16 v[80:95], v[244:247], v[100:103], v[80:95]
	ds_read_b128 v[244:247], v207 offset:57344
	v_exp_f32_e32 v168, v168
	v_exp_f32_e32 v171, v171
	v_fma_f32 v154, v76, s92, v152
	v_fma_f32 v155, v77, s92, v152
	s_waitcnt lgkmcnt(3)
	v_mfma_f32_32x32x16_bf16 v[80:95], v[248:251], v[96:99], v[80:95]
	ds_read_b128 v[248:251], v206 offset:57344
	v_exp_f32_e32 v169, v169
	v_exp_f32_e32 v170, v170
	v_fma_f32 v153, v79, s92, v152
	v_fma_f32 v152, v78, s92, v152
	s_waitcnt lgkmcnt(3)
	v_mfma_f32_32x32x16_bf16 v[64:79], v[236:239], v[124:127], 0
	ds_read_b128 v[236:239], v205 offset:57344
	v_exp_f32_e32 v158, v158
	v_exp_f32_e32 v159, v159
	v_add_f32_e32 v210, 0, v162
	s_waitcnt lgkmcnt(3)
	v_mfma_f32_32x32x16_bf16 v[64:79], v[240:243], v[120:123], v[64:79]
	ds_read_b128 v[240:243], v204 offset:57344
	v_exp_f32_e32 v156, v156
	v_exp_f32_e32 v157, v157
	v_add_f32_e32 v210, v216, v210
	s_waitcnt lgkmcnt(3)
	v_mfma_f32_32x32x16_bf16 v[64:79], v[244:247], v[116:119], v[64:79]
	ds_read_b128 v[244:247], v202 offset:57344
	v_exp_f32_e32 v150, v150
	v_exp_f32_e32 v151, v151
	v_add_f32_e32 v210, v163, v210
	s_waitcnt lgkmcnt(3)
	v_mfma_f32_32x32x16_bf16 v[64:79], v[248:251], v[112:115], v[64:79]
	ds_read_b128 v[248:251], v201 offset:57344
	v_exp_f32_e32 v148, v148
	v_exp_f32_e32 v149, v149
	v_add_f32_e32 v210, v177, v210
	s_waitcnt lgkmcnt(3)
	v_mfma_f32_32x32x16_bf16 v[64:79], v[236:239], v[108:111], v[64:79]
	v_exp_f32_e32 v146, v146
	v_exp_f32_e32 v147, v147
	v_add_f32_e32 v210, v164, v210
	s_waitcnt lgkmcnt(2)
	v_mfma_f32_32x32x16_bf16 v[64:79], v[240:243], v[104:107], v[64:79]
	v_exp_f32_e32 v160, v160
	v_exp_f32_e32 v161, v161
	v_add_f32_e32 v210, v176, v210
	s_waitcnt lgkmcnt(1)
	v_mfma_f32_32x32x16_bf16 v[64:79], v[244:247], v[100:103], v[64:79]
	v_exp_f32_e32 v154, v154
	v_exp_f32_e32 v155, v155
	v_add_f32_e32 v210, v165, v210
	s_waitcnt lgkmcnt(0)
	v_mfma_f32_32x32x16_bf16 v[64:79], v[248:251], v[96:99], v[64:79]
	v_exp_f32_e32 v152, v152
	v_exp_f32_e32 v153, v153
	v_add_f32_e32 v210, v175, v210
	s_waitcnt vmcnt(0)
	ds_write_b128 v198, v[136:139] offset:32768
	ds_write_b128 v199, v[140:143] offset:32768
	s_sub_i32 s7, s8, 64
	s_cmp_lt_u32 s6, 2
	s_cselect_b32 s6, s15, s7
	s_ashr_i32 s7, s6, 31
	s_mul_hi_u32 s100, s6, s40
	s_mul_i32 s101, s6, s41
	s_add_u32 s100, s100, s101
	s_mul_i32 s101, s7, s40
	s_add_u32 s100, s100, s101
	s_mul_i32 s6, s6, s40
	s_mov_b32 s7, s100
	s_lshl_b64 s[6:7], s[6:7], 1
	v_cvt_pk_bf16_f32 v162, v162, v216
	v_cvt_pk_bf16_f32 v163, v163, v177
	v_cvt_pk_bf16_f32 v164, v164, v176
	v_cvt_pk_bf16_f32 v165, v165, v175
	s_nop 0
	v_permlane32_swap_b32_e32 v162, v164
	v_permlane32_swap_b32_e32 v163, v165
	ds_read_b64_tr_b16 v[216:217], v193 offset:0
	ds_read_b64_tr_b16 v[218:219], v193 offset:0x800
	s_waitcnt lgkmcnt(0)
	v_mfma_f32_32x32x16_bf16 v[48:63], v[162:165], v[216:219], v[48:63]
	ds_read_b64_tr_b16 v[220:221], v193 offset:0x1000
	ds_read_b64_tr_b16 v[222:223], v193 offset:0x1800
	ds_read_b64_tr_b16 v[224:225], v193 offset:0x2000
	ds_read_b64_tr_b16 v[226:227], v193 offset:0x2800
	ds_read_b64_tr_b16 v[232:233], v193 offset:0x3000
	ds_read_b64_tr_b16 v[234:235], v193 offset:0x3800
	ds_read_b64_tr_b16 v[216:217], v193 offset:0x200
	ds_read_b64_tr_b16 v[218:219], v193 offset:0xa00
	v_add_f32_e32 v210, v166, v210
	v_add_f32_e32 v210, v173, v210
	v_add_f32_e32 v210, v167, v210
	v_add_f32_e32 v210, v172, v210
	v_add_f32_e32 v210, v168, v210
	v_add_f32_e32 v210, v171, v210
	v_add_f32_e32 v210, v169, v210
	v_cvt_pk_bf16_f32 v166, v166, v173
	v_cvt_pk_bf16_f32 v167, v167, v172
	v_cvt_pk_bf16_f32 v168, v168, v171
	v_cvt_pk_bf16_f32 v169, v169, v170
	s_nop 0
	v_permlane32_swap_b32_e32 v166, v168
	v_permlane32_swap_b32_e32 v167, v169
	s_waitcnt lgkmcnt(6)
	s_nop 0
	v_mfma_f32_32x32x16_bf16 v[48:63], v[166:169], v[220:223], v[48:63]
	ds_read_b64_tr_b16 v[220:221], v193 offset:0x1200
	ds_read_b64_tr_b16 v[222:223], v193 offset:0x1a00
	v_add_f32_e32 v210, v170, v210
	v_add_f32_e32 v210, v158, v210
	v_add_f32_e32 v210, v159, v210
	v_add_f32_e32 v210, v156, v210
	v_add_f32_e32 v210, v157, v210
	v_cvt_pk_bf16_f32 v170, v158, v159
	v_cvt_pk_bf16_f32 v171, v156, v157
	v_cvt_pk_bf16_f32 v172, v150, v151
	v_cvt_pk_bf16_f32 v173, v148, v149
	s_nop 0
	v_permlane32_swap_b32_e32 v170, v172
	v_permlane32_swap_b32_e32 v171, v173
	s_waitcnt lgkmcnt(6)
	s_nop 0
	v_mfma_f32_32x32x16_bf16 v[48:63], v[170:173], v[224:227], v[48:63]
	ds_read_b64_tr_b16 v[224:225], v193 offset:0x2200
	ds_read_b64_tr_b16 v[226:227], v193 offset:0x2a00
	v_add_f32_e32 v210, v150, v210
	v_add_f32_e32 v210, v151, v210
	v_add_f32_e32 v210, v148, v210
	v_add_f32_e32 v210, v149, v210
	v_add_f32_e32 v210, v146, v210
	v_cvt_pk_bf16_f32 v212, v146, v147
	v_cvt_pk_bf16_f32 v213, v160, v161
	v_cvt_pk_bf16_f32 v214, v154, v155
	v_cvt_pk_bf16_f32 v215, v152, v153
	s_nop 0
	v_permlane32_swap_b32_e32 v212, v214
	v_permlane32_swap_b32_e32 v213, v215
	s_waitcnt lgkmcnt(6)
	s_nop 0
	v_mfma_f32_32x32x16_bf16 v[48:63], v[212:215], v[232:235], v[48:63]
	ds_read_b64_tr_b16 v[232:233], v193 offset:0x3200
	ds_read_b64_tr_b16 v[234:235], v193 offset:0x3a00
	v_add_f32_e32 v210, v147, v210
	v_add_f32_e32 v210, v160, v210
	v_add_f32_e32 v210, v161, v210
	v_add_f32_e32 v210, v154, v210
	v_add_f32_e32 v210, v155, v210
	s_waitcnt lgkmcnt(6)
	v_mfma_f32_32x32x16_bf16 v[32:47], v[162:165], v[216:219], v[32:47]
	ds_read_b64_tr_b16 v[216:217], v193 offset:0x400
	ds_read_b64_tr_b16 v[218:219], v193 offset:0xc00
	v_add_f32_e32 v210, v152, v210
	v_add_f32_e32 v210, v153, v210
	v_mov_b32_e32 v211, v210
	s_nop 1
	v_permlane32_swap_b32_e32 v210, v211
	v_lshl_add_u64 v[146:147], s[6:7], 0, v[178:179]
	s_waitcnt lgkmcnt(6)
	v_mfma_f32_32x32x16_bf16 v[32:47], v[166:169], v[220:223], v[32:47]
	ds_read_b64_tr_b16 v[220:221], v193 offset:0x1400
	ds_read_b64_tr_b16 v[222:223], v193 offset:0x1c00
	v_lshl_add_u64 v[150:151], s[6:7], 0, v[180:181]
	v_lshl_add_u64 v[154:155], s[6:7], 0, v[182:183]
	v_lshl_add_u64 v[158:159], s[6:7], 0, v[184:185]
	v_max_f32_e32 v250, v81, v81
	v_max_f32_e32 v251, v80, v80
	global_load_dwordx4 v[146:149], v[146:147], off
	global_load_dwordx4 v[150:153], v[150:151], off
	global_load_dwordx4 v[154:157], v[154:155], off
	global_load_dwordx4 v[158:161], v[158:159], off
	s_waitcnt lgkmcnt(6)
	v_mfma_f32_32x32x16_bf16 v[32:47], v[170:173], v[224:227], v[32:47]
	ds_read_b64_tr_b16 v[224:225], v193 offset:0x2400
	ds_read_b64_tr_b16 v[226:227], v193 offset:0x2c00
	v_max_f32_e32 v250, v251, v250
	v_max3_f32 v250, v250, v82, v83
	v_max3_f32 v250, v250, v84, v85
	v_max3_f32 v250, v250, v86, v87
	v_max3_f32 v250, v250, v88, v89
	s_waitcnt lgkmcnt(6)
	v_mfma_f32_32x32x16_bf16 v[32:47], v[212:215], v[232:235], v[32:47]
	ds_read_b64_tr_b16 v[232:233], v193 offset:0x3400
	ds_read_b64_tr_b16 v[234:235], v193 offset:0x3c00
	v_max3_f32 v250, v250, v90, v91
	v_max3_f32 v250, v250, v92, v93
	v_max3_f32 v250, v250, v94, v95
	v_max3_f32 v250, v250, v64, v65
	v_max3_f32 v250, v250, v66, v67
	s_waitcnt lgkmcnt(6)
	v_mfma_f32_32x32x16_bf16 v[16:31], v[162:165], v[216:219], v[16:31]
	ds_read_b64_tr_b16 v[216:217], v193 offset:0x600
	ds_read_b64_tr_b16 v[218:219], v193 offset:0xe00
	v_max3_f32 v250, v250, v68, v69
	v_max3_f32 v250, v250, v70, v71
	v_max3_f32 v250, v250, v72, v73
	v_max3_f32 v250, v250, v74, v75
	v_max3_f32 v250, v250, v76, v77
	s_waitcnt lgkmcnt(6)
	v_mfma_f32_32x32x16_bf16 v[16:31], v[166:169], v[220:223], v[16:31]
	ds_read_b64_tr_b16 v[220:221], v193 offset:0x1600
	ds_read_b64_tr_b16 v[222:223], v193 offset:0x1e00
	v_max3_f32 v250, v250, v78, v79
	v_mov_b32_e32 v251, v250
	s_nop 1
	v_permlane32_swap_b32_e32 v250, v251
	v_max_f32_e32 v251, v251, v251
	v_max_f32_e32 v250, v250, v250
	s_waitcnt lgkmcnt(6)
	v_mfma_f32_32x32x16_bf16 v[16:31], v[170:173], v[224:227], v[16:31]
	ds_read_b64_tr_b16 v[224:225], v193 offset:0x2600
	ds_read_b64_tr_b16 v[226:227], v193 offset:0x2e00
	v_max_f32_e32 v250, v250, v251
	v_sub_f32_e32 v251, v250, v174
	v_cmp_ge_f32_e32 vcc, s93, v251
	v_max_f32_e32 v251, v174, v174
	v_max_f32_e32 v250, v251, v250
	s_waitcnt lgkmcnt(6)
	v_mfma_f32_32x32x16_bf16 v[16:31], v[212:215], v[232:235], v[16:31]
	ds_read_b64_tr_b16 v[232:233], v193 offset:0x3600
	ds_read_b64_tr_b16 v[234:235], v193 offset:0x3e00
	v_sub_f32_e32 v251, v174, v250
	v_mul_f32_e32 v251, 0x3e0293ee, v251
	v_exp_f32_e32 v251, v251
	s_waitcnt lgkmcnt(6)
	v_mfma_f32_32x32x16_bf16 v[0:15], v[162:165], v[216:219], v[0:15]
	s_waitcnt lgkmcnt(4)
	v_mfma_f32_32x32x16_bf16 v[0:15], v[166:169], v[220:223], v[0:15]
	s_waitcnt lgkmcnt(2)
	v_mfma_f32_32x32x16_bf16 v[0:15], v[170:173], v[224:227], v[0:15]
	s_waitcnt lgkmcnt(0)
	v_mfma_f32_32x32x16_bf16 v[0:15], v[212:215], v[232:235], v[0:15]
	s_cmp_eq_u64 vcc, exec
	s_cselect_b64 s[6:7], -1, 0

.LBB0_743:
	v_cndmask_b32_e64 v216, v250, v174, s[6:7]
	v_mul_f32_e32 v212, 0xbe0293ee, v216
	v_fmamk_f32 v162, v80, 0x3e0293ee, v212
	v_fmamk_f32 v177, v81, 0x3e0293ee, v212
	v_fmamk_f32 v163, v82, 0x3e0293ee, v212
	v_fmamk_f32 v176, v83, 0x3e0293ee, v212
	v_fmamk_f32 v164, v84, 0x3e0293ee, v212
	v_fmamk_f32 v175, v85, 0x3e0293ee, v212
	v_fmamk_f32 v165, v86, 0x3e0293ee, v212
	v_fmamk_f32 v174, v87, 0x3e0293ee, v212
	v_fmamk_f32 v166, v88, 0x3e0293ee, v212
	v_fmamk_f32 v173, v89, 0x3e0293ee, v212
	v_fmamk_f32 v167, v90, 0x3e0293ee, v212
	v_fmamk_f32 v172, v91, 0x3e0293ee, v212
	v_fmamk_f32 v168, v92, 0x3e0293ee, v212
	v_fmamk_f32 v171, v93, 0x3e0293ee, v212
	v_fmamk_f32 v169, v94, 0x3e0293ee, v212
	v_fmamk_f32 v170, v95, 0x3e0293ee, v212
	ds_read_b128 v[240:243], v200 offset:32768
	ds_read_b128 v[244:247], v208 offset:32768
	ds_read_b128 v[248:251], v207 offset:32768
	s_waitcnt lgkmcnt(2)
	v_mfma_f32_32x32x16_bf16 v[80:95], v[240:243], v[124:127], 0
	ds_read_b128 v[240:243], v206 offset:32768
	v_exp_f32_e32 v162, v162
	v_exp_f32_e32 v177, v177
	v_fmamk_f32 v219, v70, 0x3e0293ee, v212
	s_waitcnt lgkmcnt(2)
	v_mfma_f32_32x32x16_bf16 v[80:95], v[244:247], v[120:123], v[80:95]
	ds_read_b128 v[244:247], v205 offset:32768
	v_exp_f32_e32 v163, v163
	v_exp_f32_e32 v176, v176
	v_fmamk_f32 v220, v71, 0x3e0293ee, v212
	s_waitcnt lgkmcnt(2)
	v_mfma_f32_32x32x16_bf16 v[80:95], v[248:251], v[116:119], v[80:95]
	ds_read_b128 v[248:251], v204 offset:32768
	v_exp_f32_e32 v164, v164
	v_exp_f32_e32 v175, v175
	v_fmamk_f32 v225, v64, 0x3e0293ee, v212
	s_waitcnt lgkmcnt(2)
	v_mfma_f32_32x32x16_bf16 v[80:95], v[240:243], v[112:115], v[80:95]
	ds_read_b128 v[240:243], v202 offset:32768
	v_exp_f32_e32 v165, v165
	v_exp_f32_e32 v174, v174
	v_fmamk_f32 v226, v65, 0x3e0293ee, v212
	s_waitcnt lgkmcnt(2)
	v_mfma_f32_32x32x16_bf16 v[80:95], v[244:247], v[108:111], v[80:95]
	ds_read_b128 v[244:247], v201 offset:32768
	v_exp_f32_e32 v166, v166
	v_exp_f32_e32 v173, v173
	v_fmamk_f32 v227, v66, 0x3e0293ee, v212
	s_waitcnt lgkmcnt(2)
	v_mfma_f32_32x32x16_bf16 v[80:95], v[248:251], v[104:107], v[80:95]
	ds_read_b128 v[248:251], v200 offset:40960
	v_exp_f32_e32 v167, v167
	v_exp_f32_e32 v172, v172
	v_fmamk_f32 v232, v67, 0x3e0293ee, v212
	s_waitcnt lgkmcnt(2)
	v_mfma_f32_32x32x16_bf16 v[80:95], v[240:243], v[100:103], v[80:95]
	ds_read_b128 v[240:243], v208 offset:40960
	v_exp_f32_e32 v168, v168
	v_exp_f32_e32 v171, v171
	v_fmamk_f32 v233, v68, 0x3e0293ee, v212
	s_waitcnt lgkmcnt(2)
	v_mfma_f32_32x32x16_bf16 v[80:95], v[244:247], v[96:99], v[80:95]
	ds_read_b128 v[244:247], v207 offset:40960
	v_exp_f32_e32 v169, v169
	v_exp_f32_e32 v170, v170
	v_fmamk_f32 v218, v69, 0x3e0293ee, v212
	v_fmamk_f32 v221, v72, 0x3e0293ee, v212
	v_fmamk_f32 v222, v73, 0x3e0293ee, v212
	v_fmamk_f32 v223, v74, 0x3e0293ee, v212
	v_fmamk_f32 v224, v75, 0x3e0293ee, v212
	v_fmamk_f32 v213, v76, 0x3e0293ee, v212
	v_fmamk_f32 v234, v77, 0x3e0293ee, v212
	v_fmamk_f32 v235, v78, 0x3e0293ee, v212
	v_fmac_f32_e32 v212, 0x3e0293ee, v79
	s_waitcnt lgkmcnt(2)
	v_mfma_f32_32x32x16_bf16 v[64:79], v[248:251], v[124:127], 0
	ds_read_b128 v[248:251], v206 offset:40960
	v_exp_f32_e32 v215, v226
	v_exp_f32_e32 v226, v232
	s_waitcnt lgkmcnt(2)
	v_mfma_f32_32x32x16_bf16 v[64:79], v[240:243], v[120:123], v[64:79]
	ds_read_b128 v[240:243], v205 offset:40960
	v_exp_f32_e32 v232, v219
	v_add_f32_e32 v219, 0, v162
	v_add_f32_e32 v219, v177, v219
	v_add_f32_e32 v219, v163, v219
	s_waitcnt lgkmcnt(2)
	v_mfma_f32_32x32x16_bf16 v[64:79], v[244:247], v[116:119], v[64:79]
	ds_read_b128 v[244:247], v204 offset:40960
	v_add_f32_e32 v219, v176, v219
	v_add_f32_e32 v219, v164, v219
	v_add_f32_e32 v219, v175, v219
	v_add_f32_e32 v219, v165, v219
	v_add_f32_e32 v219, v174, v219
	s_waitcnt lgkmcnt(2)
	v_mfma_f32_32x32x16_bf16 v[64:79], v[248:251], v[112:115], v[64:79]
	ds_read_b128 v[248:251], v202 offset:40960
	v_add_f32_e32 v219, v166, v219
	v_add_f32_e32 v219, v173, v219
	v_add_f32_e32 v219, v167, v219
	v_add_f32_e32 v219, v172, v219
	v_add_f32_e32 v219, v168, v219
	s_waitcnt lgkmcnt(2)
	v_mfma_f32_32x32x16_bf16 v[64:79], v[240:243], v[108:111], v[64:79]
	ds_read_b128 v[240:243], v201 offset:40960
	v_exp_f32_e32 v214, v225
	v_add_f32_e32 v219, v171, v219
	v_exp_f32_e32 v225, v227
	s_waitcnt lgkmcnt(2)
	v_mfma_f32_32x32x16_bf16 v[64:79], v[244:247], v[104:107], v[64:79]
	v_add_f32_e32 v219, v169, v219
	v_add_f32_e32 v219, v170, v219
	v_exp_f32_e32 v227, v233
	v_add_f32_e32 v219, v214, v219
	s_waitcnt lgkmcnt(1)
	v_mfma_f32_32x32x16_bf16 v[64:79], v[248:251], v[100:103], v[64:79]
	v_exp_f32_e32 v218, v218
	v_add_f32_e32 v219, v215, v219
	v_add_f32_e32 v219, v225, v219
	v_add_f32_e32 v219, v226, v219
	s_waitcnt lgkmcnt(0)
	v_mfma_f32_32x32x16_bf16 v[64:79], v[240:243], v[96:99], v[64:79]
	v_exp_f32_e32 v233, v220
	v_exp_f32_e32 v221, v221
	v_add_f32_e32 v219, v227, v219
	s_cmp_ge_u32 s14, s91
	s_cselect_b64 s[10:11], -1, 0
	s_waitcnt vmcnt(0)
	ds_write_b128 v198, v[154:157] offset:49152
	ds_write_b128 v199, v[158:161] offset:49152
	s_ashr_i32 s9, s8, 31
	s_mul_hi_u32 s100, s8, s40
	s_mul_i32 s101, s8, s41
	s_add_u32 s100, s100, s101
	s_mul_i32 s101, s9, s40
	s_add_u32 s100, s100, s101
	s_mul_i32 s6, s8, s40
	s_mov_b32 s7, s100
	s_lshl_b64 s[6:7], s[6:7], 1
	v_exp_f32_e32 v222, v222
	v_add_f32_e32 v219, v218, v219
	v_exp_f32_e32 v223, v223
	v_add_f32_e32 v219, v232, v219
	v_exp_f32_e32 v224, v224
	v_add_f32_e32 v219, v233, v219
	v_exp_f32_e32 v213, v213
	v_add_f32_e32 v219, v221, v219
	v_exp_f32_e32 v234, v234
	v_add_f32_e32 v219, v222, v219
	v_exp_f32_e32 v235, v235
	v_add_f32_e32 v219, v223, v219
	v_exp_f32_e32 v212, v212
	v_add_f32_e32 v219, v224, v219
	v_add_f32_e32 v219, v213, v219
	v_add_f32_e32 v219, v234, v219
	v_add_f32_e32 v219, v235, v219
	v_add_f32_e32 v219, v212, v219
	v_cvt_pk_bf16_f32 v162, v162, v177
	v_cvt_pk_bf16_f32 v163, v163, v176
	v_cvt_pk_bf16_f32 v164, v164, v175
	v_cvt_pk_bf16_f32 v165, v165, v174
	v_cvt_pk_bf16_f32 v169, v169, v170
	v_cvt_pk_bf16_f32 v170, v214, v215
	v_cvt_pk_bf16_f32 v176, v213, v234
	v_cvt_pk_bf16_f32 v177, v235, v212
	v_permlane32_swap_b32_e32 v162, v164
	v_permlane32_swap_b32_e32 v163, v165
	ds_read_b64_tr_b16 v[212:213], v197 offset:0
	ds_read_b64_tr_b16 v[214:215], v197 offset:0x800
	s_waitcnt lgkmcnt(0)
	v_mfma_f32_32x32x16_bf16 v[48:63], v[162:165], v[212:215], v[48:63]
	v_mov_b32_e32 v220, v219
	s_nop 1
	v_permlane32_swap_b32_e32 v219, v220
	v_cvt_pk_bf16_f32 v166, v166, v173
	v_cvt_pk_bf16_f32 v167, v167, v172
	v_cvt_pk_bf16_f32 v168, v168, v171
	v_cvt_pk_bf16_f32 v171, v225, v226
	v_cvt_pk_bf16_f32 v174, v221, v222
	v_cvt_pk_bf16_f32 v175, v223, v224
	v_permlane32_swap_b32_e32 v166, v168
	v_permlane32_swap_b32_e32 v167, v169
	ds_read_b64_tr_b16 v[222:223], v197 offset:0x1000
	ds_read_b64_tr_b16 v[224:225], v197 offset:0x1800
	s_waitcnt lgkmcnt(0)
	v_mfma_f32_32x32x16_bf16 v[48:63], v[166:169], v[222:225], v[48:63]
	v_cvt_pk_bf16_f32 v172, v227, v218
	v_cvt_pk_bf16_f32 v173, v232, v233
	s_nop 0
	v_permlane32_swap_b32_e32 v170, v172
	v_permlane32_swap_b32_e32 v171, v173
	v_permlane32_swap_b32_e32 v174, v176
	ds_read_b64_tr_b16 v[232:233], v197 offset:0x2000
	ds_read_b64_tr_b16 v[234:235], v197 offset:0x2800
	ds_read_b64_tr_b16 v[236:237], v197 offset:0x3000
	ds_read_b64_tr_b16 v[238:239], v197 offset:0x3800
	ds_read_b64_tr_b16 v[212:213], v197 offset:0x200
	ds_read_b64_tr_b16 v[214:215], v197 offset:0xa00
	ds_read_b64_tr_b16 v[222:223], v197 offset:0x1200
	ds_read_b64_tr_b16 v[224:225], v197 offset:0x1a00
	s_waitcnt lgkmcnt(6)
	v_mfma_f32_32x32x16_bf16 v[48:63], v[170:173], v[232:235], v[48:63]
	ds_read_b64_tr_b16 v[232:233], v197 offset:0x2200
	ds_read_b64_tr_b16 v[234:235], v197 offset:0x2a00
	v_permlane32_swap_b32_e32 v175, v177
	v_lshl_add_u64 v[128:129], s[6:7], 0, v[178:179]
	v_lshl_add_u64 v[132:133], s[6:7], 0, v[180:181]
	v_lshl_add_u64 v[136:137], s[6:7], 0, v[182:183]
	v_lshl_add_u64 v[140:141], s[6:7], 0, v[184:185]
	s_waitcnt lgkmcnt(6)
	v_mfma_f32_32x32x16_bf16 v[48:63], v[174:177], v[236:239], v[48:63]
	ds_read_b64_tr_b16 v[236:237], v197 offset:0x3200
	ds_read_b64_tr_b16 v[238:239], v197 offset:0x3a00
	v_max_f32_e32 v250, v81, v81
	v_max_f32_e32 v251, v80, v80
	v_max_f32_e32 v250, v251, v250
	v_max3_f32 v250, v250, v82, v83
	v_max3_f32 v250, v250, v84, v85
	s_waitcnt lgkmcnt(6)
	v_mfma_f32_32x32x16_bf16 v[32:47], v[162:165], v[212:215], v[32:47]
	ds_read_b64_tr_b16 v[212:213], v197 offset:0x400
	ds_read_b64_tr_b16 v[214:215], v197 offset:0xc00
	v_max3_f32 v250, v250, v86, v87
	v_max3_f32 v250, v250, v88, v89
	v_max3_f32 v250, v250, v90, v91
	v_max3_f32 v250, v250, v92, v93
	v_max3_f32 v250, v250, v94, v95
	s_waitcnt lgkmcnt(6)
	v_mfma_f32_32x32x16_bf16 v[32:47], v[166:169], v[222:225], v[32:47]
	ds_read_b64_tr_b16 v[222:223], v197 offset:0x1400
	ds_read_b64_tr_b16 v[224:225], v197 offset:0x1c00
	v_max3_f32 v250, v250, v64, v65
	v_max3_f32 v250, v250, v66, v67
	v_max3_f32 v250, v250, v68, v69
	v_max3_f32 v250, v250, v70, v71
	v_max3_f32 v250, v250, v72, v73
	global_load_dwordx4 v[128:131], v[128:129], off
	global_load_dwordx4 v[132:135], v[132:133], off
	global_load_dwordx4 v[136:139], v[136:137], off
	global_load_dwordx4 v[140:143], v[140:141], off
	s_waitcnt lgkmcnt(6)
	v_mfma_f32_32x32x16_bf16 v[32:47], v[170:173], v[232:235], v[32:47]
	ds_read_b64_tr_b16 v[232:233], v197 offset:0x2400
	ds_read_b64_tr_b16 v[234:235], v197 offset:0x2c00
	v_max3_f32 v250, v250, v74, v75
	v_max3_f32 v250, v250, v76, v77
	v_max3_f32 v250, v250, v78, v79
	v_mov_b32_e32 v251, v250
	s_nop 1
	v_permlane32_swap_b32_e32 v250, v251
	s_waitcnt lgkmcnt(6)
	v_mfma_f32_32x32x16_bf16 v[32:47], v[174:177], v[236:239], v[32:47]
	ds_read_b64_tr_b16 v[236:237], v197 offset:0x3400
	ds_read_b64_tr_b16 v[238:239], v197 offset:0x3c00
	v_max_f32_e32 v251, v251, v251
	v_max_f32_e32 v250, v250, v250
	v_max_f32_e32 v250, v250, v251
	v_sub_f32_e32 v251, v250, v216
	v_cmp_ge_f32_e32 vcc, s93, v251
	s_waitcnt lgkmcnt(6)
	v_mfma_f32_32x32x16_bf16 v[16:31], v[162:165], v[212:215], v[16:31]
	ds_read_b64_tr_b16 v[212:213], v197 offset:0x600
	ds_read_b64_tr_b16 v[214:215], v197 offset:0xe00
	v_max_f32_e32 v251, v216, v216
	v_max_f32_e32 v250, v251, v250
	v_sub_f32_e32 v251, v216, v250
	v_mul_f32_e32 v251, 0x3e0293ee, v251
	s_waitcnt lgkmcnt(6)
	v_mfma_f32_32x32x16_bf16 v[16:31], v[166:169], v[222:225], v[16:31]
	ds_read_b64_tr_b16 v[222:223], v197 offset:0x1600
	ds_read_b64_tr_b16 v[224:225], v197 offset:0x1e00
	v_exp_f32_e32 v251, v251
	s_waitcnt lgkmcnt(6)
	v_mfma_f32_32x32x16_bf16 v[16:31], v[170:173], v[232:235], v[16:31]
	ds_read_b64_tr_b16 v[232:233], v197 offset:0x2600
	ds_read_b64_tr_b16 v[234:235], v197 offset:0x2e00
	s_waitcnt lgkmcnt(6)
	v_mfma_f32_32x32x16_bf16 v[16:31], v[174:177], v[236:239], v[16:31]
	ds_read_b64_tr_b16 v[236:237], v197 offset:0x3600
	ds_read_b64_tr_b16 v[238:239], v197 offset:0x3e00
	s_waitcnt lgkmcnt(6)
	v_mfma_f32_32x32x16_bf16 v[0:15], v[162:165], v[212:215], v[0:15]
	s_waitcnt lgkmcnt(4)
	v_mfma_f32_32x32x16_bf16 v[0:15], v[166:169], v[222:225], v[0:15]
	s_waitcnt lgkmcnt(2)
	v_mfma_f32_32x32x16_bf16 v[0:15], v[170:173], v[232:235], v[0:15]
	s_waitcnt lgkmcnt(0)
	v_mfma_f32_32x32x16_bf16 v[0:15], v[174:177], v[236:239], v[0:15]
	s_cmp_eq_u64 vcc, exec
	s_cselect_b64 s[6:7], -1, 0
	s_barrier
	v_cndmask_b32_e64 v218, v251, 1.0, s[6:7]
	v_cmp_gt_f32_e32 vcc, 1.0, v218
	ds_write_b128 v195, v[146:149] offset:16384
	ds_write_b128 v196, v[150:153] offset:16384
	s_cbranch_vccz .LBB0_749
	s_and_saveexec_b64 s[12:13], s[4:5]
	ds_write_b32 v194, v218 offset:128
	s_or_b64 exec, exec, s[12:13]
	s_waitcnt lgkmcnt(0)
	v_add_u32_e32 v158, v192, v144
	ds_read_b128 v[146:149], v158 offset:224
	ds_read_b128 v[150:153], v158 offset:192
	ds_read_b128 v[154:157], v158 offset:160
	ds_read_b128 v[158:161], v158 offset:128
	s_waitcnt lgkmcnt(3)
	v_pk_mul_f32 v[60:61], v[60:61], v[146:147]
	s_waitcnt lgkmcnt(2)
	v_pk_mul_f32 v[56:57], v[56:57], v[150:151]
	s_waitcnt lgkmcnt(1)
	v_pk_mul_f32 v[52:53], v[52:53], v[154:155]
	v_pk_mul_f32 v[62:63], v[62:63], v[148:149]
	v_pk_mul_f32 v[58:59], v[58:59], v[152:153]
	v_pk_mul_f32 v[54:55], v[54:55], v[156:157]
	s_waitcnt lgkmcnt(0)
	v_pk_mul_f32 v[50:51], v[50:51], v[160:161]
	v_pk_mul_f32 v[48:49], v[48:49], v[158:159]
	v_pk_mul_f32 v[44:45], v[44:45], v[146:147]
	v_pk_mul_f32 v[40:41], v[40:41], v[150:151]
	v_pk_mul_f32 v[36:37], v[36:37], v[154:155]
	v_pk_mul_f32 v[46:47], v[46:47], v[148:149]
	v_pk_mul_f32 v[42:43], v[42:43], v[152:153]
	v_pk_mul_f32 v[38:39], v[38:39], v[156:157]
	v_pk_mul_f32 v[34:35], v[34:35], v[160:161]
	v_pk_mul_f32 v[32:33], v[32:33], v[158:159]
	v_pk_mul_f32 v[28:29], v[28:29], v[146:147]
	v_pk_mul_f32 v[24:25], v[24:25], v[150:151]
	v_pk_mul_f32 v[20:21], v[20:21], v[154:155]
	v_pk_mul_f32 v[30:31], v[30:31], v[148:149]
	v_pk_mul_f32 v[26:27], v[26:27], v[152:153]
	v_pk_mul_f32 v[22:23], v[22:23], v[156:157]
	v_pk_mul_f32 v[18:19], v[18:19], v[160:161]
	v_pk_mul_f32 v[16:17], v[16:17], v[158:159]
	v_pk_mul_f32 v[12:13], v[12:13], v[146:147]
	v_pk_mul_f32 v[8:9], v[8:9], v[150:151]
	v_pk_mul_f32 v[4:5], v[4:5], v[154:155]
	v_pk_mul_f32 v[14:15], v[14:15], v[148:149]
	v_pk_mul_f32 v[10:11], v[10:11], v[152:153]
	v_pk_mul_f32 v[6:7], v[6:7], v[156:157]
	v_pk_mul_f32 v[2:3], v[2:3], v[160:161]
	v_pk_mul_f32 v[0:1], v[0:1], v[158:159]

.LBB0_761:
	v_mbcnt_lo_u32_b32 v0, -1, 0
	v_mbcnt_hi_u32_b32 v0, -1, v0
	s_add_i32 s4, 0, 0x10000
	v_add_u32_e32 v0, s66, v0
	s_cmp_lg_u32 0, -1
	v_ashrrev_i32_e32 v178, 6, v0
	v_and_b32_e32 v179, 31, v0
	v_lshlrev_b32_e32 v175, 5, v178
	v_or_b32_e32 v2, s86, v179
	v_add_u32_e32 v2, v2, v175
	v_and_b32_e32 v1, 0x3fffffc0, v0
	v_ashrrev_i32_e32 v3, 31, v2
	v_lshl_add_u32 v180, v1, 2, s4
	v_mul_lo_u32 v4, s40, v3
	v_mul_lo_u32 v5, s41, v2
	v_mad_u64_u32 v[2:3], s[4:5], s40, v2, 0
	v_add3_u32 v3, v3, v4, v5
	v_bfe_u32 v177, v0, 5, 1
	v_lshlrev_b64 v[2:3], 1, v[2:3]
	v_lshl_add_u64 v[4:5], s[88:89], 0, v[2:3]
	v_lshlrev_b32_e32 v144, 4, v177
	v_lshl_add_u64 v[2:3], s[72:73], 0, v[2:3]
	v_lshl_add_u64 v[4:5], v[4:5], 0, v[144:145]
	v_lshl_add_u64 v[6:7], v[2:3], 0, v[144:145]
	global_load_dwordx4 v[124:127], v[4:5], off
	global_load_dwordx4 v[120:123], v[4:5], off offset:32
	global_load_dwordx4 v[116:119], v[4:5], off offset:64
	global_load_dwordx4 v[112:115], v[4:5], off offset:96
	global_load_dwordx4 v[108:111], v[4:5], off offset:128
	global_load_dwordx4 v[104:107], v[4:5], off offset:160
	global_load_dwordx4 v[100:103], v[4:5], off offset:192
	global_load_dwordx4 v[96:99], v[4:5], off offset:224
	v_and_b32_e32 v174, 63, v0
	global_load_dwordx4 v[2:5], v[6:7], off
	v_lshl_add_u32 v1, v178, 12, s53
	v_lshlrev_b32_e32 v8, 4, v174
	v_add_u32_e32 v182, v1, v8
	v_ashrrev_i32_e32 v162, 4, v0
	v_lshlrev_b32_e32 v56, 3, v0
	v_and_b32_e32 v1, 0x78, v56
	v_lshlrev_b32_e32 v48, 1, v1
	v_and_b32_e32 v1, 48, v48
	v_add_u32_e32 v23, 32, v162
	v_ashrrev_i32_e32 v163, 31, v162
	s_cselect_b32 s6, 0, 0
	s_ashr_i32 s83, s82, 31
	v_lshl_add_u64 v[166:167], v[162:163], 0, 32
	v_ashrrev_i32_e32 v164, 3, v0
	v_ashrrev_i32_e32 v165, 31, v164
	v_lshl_add_u64 v[18:19], v[164:165], 0, s[82:83]
	v_mov_b64_e32 v[52:53], s[0:1]
	v_mad_u64_u32 v[20:21], s[4:5], v18, s3, v[52:53]
	v_lshlrev_b32_e32 v176, 4, v0
	v_mov_b32_e32 v49, v145
	v_mad_i32_i24 v21, v19, s3, v21
	v_and_b32_e32 v50, 0x70, v176
	v_mov_b32_e32 v51, v145
	v_lshl_add_u64 v[18:19], v[20:21], 0, v[50:51]
	global_load_dwordx4 v[18:21], v[18:19], off
	v_lshlrev_b32_e32 v57, 8, v179
	v_or_b32_e32 v68, 32, v144
	v_bitop3_b32 v58, v68, v57, v50 bitop3:0xde
	v_add_u32_e32 v191, 0, v58
	v_or_b32_e32 v69, 64, v144
	v_or_b32_e32 v70, 0x60, v144
	v_lshlrev_b32_e32 v71, 7, v179
	v_and_b32_e32 v72, 0x70, v56
	v_bitop3_b32 v198, v144, v71, v72 bitop3:0xde
	v_bitop3_b32 v200, v68, v71, v72 bitop3:0xde
	v_bitop3_b32 v202, v69, v71, v72 bitop3:0xde
	v_bitop3_b32 v204, v70, v71, v72 bitop3:0xde
	s_mov_b32 s8, 0
	s_mov_b32 s9, s8
	s_mov_b32 s10, s8
	s_mov_b32 s11, s8
	s_mov_b32 s12, s8
	s_mov_b32 s13, s8
	s_mov_b32 s14, s8
	s_mov_b32 s15, s8
	s_mov_b32 s16, s8
	s_mov_b32 s17, s8
	s_mov_b32 s18, s8
	s_mov_b32 s19, s8
	s_mov_b32 s20, s8
	s_mov_b32 s21, s8
	s_mov_b32 s22, s8
	s_mov_b32 s23, s8
	v_lshl_add_u64 v[168:169], s[80:81], 0, v[48:49]
	v_lshl_add_u64 v[170:171], s[78:79], 0, v[48:49]
	v_lshl_add_u64 v[172:173], s[0:1], 0, v[50:51]
	s_mov_b32 s24, 2
	v_lshl_add_u32 v183, v179, 2, v180
	v_mov_b32_e32 v197, 0
	s_waitcnt vmcnt(0)
	ds_write_b128 v182, v[2:5]
	global_load_dwordx4 v[2:5], v[6:7], off offset:32
	s_waitcnt vmcnt(0)
	ds_write_b128 v182, v[2:5] offset:1024
	global_load_dwordx4 v[2:5], v[6:7], off offset:64
	s_waitcnt vmcnt(0)
	ds_write_b128 v182, v[2:5] offset:2048
	global_load_dwordx4 v[2:5], v[6:7], off offset:96
	v_lshl_add_u64 v[6:7], v[166:167], 0, s[82:83]
	v_mul_lo_u32 v9, v6, s41
	s_waitcnt vmcnt(0)
	ds_write_b128 v182, v[2:5] offset:3072
	v_and_b32_e32 v2, 0xfffff0, v162
	v_lshlrev_b32_e32 v3, 1, v162
	v_and_or_b32 v2, v3, 8, v2
	v_lshrrev_b32_e32 v3, 1, v162
	v_lshrrev_b32_e32 v2, 1, v2
	v_bfe_u32 v4, v56, 5, 2
	v_and_b32_e32 v5, 3, v162
	v_or_b32_e32 v2, v2, v4
	v_and_or_b32 v3, v3, 4, v5
	v_lshlrev_b32_e32 v2, 9, v2
	v_lshlrev_b32_e32 v3, 6, v3
	v_or3_b32 v22, v2, v3, v1
	v_and_b32_e32 v2, 0xfffff0, v23
	v_lshlrev_b32_e32 v5, 1, v23
	v_and_or_b32 v2, v5, 8, v2
	v_lshrrev_b32_e32 v2, 1, v2
	v_or_b32_e32 v2, v2, v4
	v_lshlrev_b32_e32 v2, 9, v2
	v_or3_b32 v1, v2, v3, v1
	v_lshlrev_b32_e32 v2, 3, v174
	v_and_b32_e32 v3, 0xc0, v8
	v_lshlrev_b32_e32 v4, 1, v0
	v_and_or_b32 v3, v2, 24, v3
	v_and_b32_e32 v4, 32, v4
	v_and_b32_e32 v2, 0x100, v2
	v_or3_b32 v54, v3, v4, v2
	v_lshl_add_u64 v[2:3], v[162:163], 0, s[82:83]
	v_mul_lo_u32 v4, v3, s40
	v_mul_lo_u32 v5, v2, s41
	v_mad_u64_u32 v[2:3], s[4:5], v2, s40, 0
	v_mul_lo_u32 v8, v7, s40
	v_mad_u64_u32 v[6:7], s[4:5], v6, s40, 0
	v_add3_u32 v3, v3, v5, v4
	v_add3_u32 v7, v7, v9, v8
	v_lshlrev_b64 v[10:11], 1, v[2:3]
	v_lshlrev_b64 v[14:15], 1, v[6:7]
	v_lshl_add_u64 v[2:3], s[80:81], 0, v[10:11]
	v_lshl_add_u64 v[6:7], s[80:81], 0, v[14:15]
	v_lshl_add_u64 v[10:11], s[78:79], 0, v[10:11]
	v_lshl_add_u64 v[14:15], s[78:79], 0, v[14:15]
	v_lshl_add_u64 v[2:3], v[2:3], 0, v[48:49]
	v_lshl_add_u64 v[6:7], v[6:7], 0, v[48:49]
	v_lshl_add_u64 v[10:11], v[10:11], 0, v[48:49]
	v_lshl_add_u64 v[14:15], v[14:15], 0, v[48:49]
	global_load_dwordx4 v[2:5], v[2:3], off
	v_add_u32_e32 v186, 0, v1
	global_load_dwordx4 v[6:9], v[6:7], off
	v_lshlrev_b32_e32 v1, 8, v162
	global_load_dwordx4 v[10:13], v[10:11], off
	v_and_b32_e32 v0, 0x70, v0
	global_load_dwordx4 v[14:17], v[14:15], off
	v_bitop3_b32 v1, v48, v1, v0 bitop3:0xde
	v_add_u32_e32 v187, 0, v1
	v_lshlrev_b32_e32 v1, 8, v23
	v_bitop3_b32 v1, v48, v1, v0 bitop3:0xde
	v_add_u32_e32 v188, 0, v1
	v_lshlrev_b32_e32 v1, 7, v164
	v_bitop3_b32 v55, v50, v1, v0 bitop3:0xde
	s_add_i32 s4, 0, 0x10800
	v_add_u32_e32 v185, 0, v22
	v_add_u32_e32 v0, s4, v55
	s_waitcnt vmcnt(0)
	v_add_u32_e32 v199, s4, v198
	v_add_u32_e32 v201, s4, v200
	v_add_u32_e32 v203, s4, v202
	v_add_u32_e32 v205, s4, v204
	v_add_u32_e32 v208, 0, v55
	v_add_u32_e32 v181, s6, v54
	v_add_u32_e32 v209, 0x12800, v208
	s_waitcnt vmcnt(3)
	ds_write_b128 v185, v[2:5]
	s_waitcnt vmcnt(2)
	ds_write_b128 v186, v[6:9]
	s_waitcnt vmcnt(1)
	ds_write_b128 v187, v[10:13] offset:32768
	s_waitcnt vmcnt(0)
	ds_write_b128 v188, v[14:17] offset:32768
	ds_write_b128 v0, v[18:21]
	v_bitop3_b32 v0, v144, v57, v50 bitop3:0xde
	v_add_u32_e32 v189, 0, v0
	s_waitcnt lgkmcnt(0)
	s_barrier
	ds_read_b128 v[16:19], v189 offset:32768
	ds_read_b128 v[20:23], v189 offset:40960
	s_waitcnt lgkmcnt(1)
	v_mfma_f32_32x32x16_bf16 v[32:47], v[16:19], v[124:127], 0
	ds_read_b128 v[58:61], v191 offset:32768
	ds_read_b128 v[62:65], v191 offset:40960
	v_mov_b64_e32 v[0:1], s[8:9]
	v_mov_b64_e32 v[2:3], s[10:11]
	v_mov_b64_e32 v[4:5], s[12:13]
	v_mov_b64_e32 v[6:7], s[14:15]
	v_mov_b64_e32 v[8:9], s[16:17]
	v_mov_b64_e32 v[10:11], s[18:19]
	s_waitcnt lgkmcnt(2)
	v_mfma_f32_32x32x16_bf16 v[16:31], v[20:23], v[124:127], 0
	v_mov_b64_e32 v[12:13], s[20:21]
	v_mov_b64_e32 v[14:15], s[22:23]
	s_waitcnt lgkmcnt(1)
	v_mfma_f32_32x32x16_bf16 v[32:47], v[58:61], v[120:123], v[32:47]
	v_bitop3_b32 v58, v69, v57, v50 bitop3:0xde
	v_add_u32_e32 v193, 0, v58
	s_waitcnt lgkmcnt(0)
	v_mfma_f32_32x32x16_bf16 v[16:31], v[62:65], v[120:123], v[16:31]
	ds_read_b128 v[58:61], v193 offset:32768
	ds_read_b128 v[62:65], v193 offset:40960
	s_waitcnt lgkmcnt(1)
	v_mfma_f32_32x32x16_bf16 v[32:47], v[58:61], v[116:119], v[32:47]
	v_bitop3_b32 v58, v70, v57, v50 bitop3:0xde
	v_add_u32_e32 v195, 0, v58
	s_waitcnt lgkmcnt(0)
	v_mfma_f32_32x32x16_bf16 v[16:31], v[62:65], v[116:119], v[16:31]
	ds_read_b128 v[58:61], v195 offset:32768
	ds_read_b128 v[62:65], v195 offset:40960
	s_waitcnt lgkmcnt(1)
	v_mfma_f32_32x32x16_bf16 v[32:47], v[58:61], v[112:115], v[32:47]
	v_or_b32_e32 v58, 0x80, v144
	v_bitop3_b32 v58, v58, v57, v50 bitop3:0xde
	v_add_u32_e32 v196, 0, v58
	s_waitcnt lgkmcnt(0)
	v_mfma_f32_32x32x16_bf16 v[16:31], v[62:65], v[112:115], v[16:31]
	ds_read_b128 v[58:61], v196 offset:32768
	ds_read_b128 v[62:65], v196 offset:40960
	s_waitcnt lgkmcnt(1)
	v_mfma_f32_32x32x16_bf16 v[32:47], v[58:61], v[108:111], v[32:47]
	v_or_b32_e32 v58, 0xa0, v144
	v_bitop3_b32 v58, v58, v57, v50 bitop3:0xde
	v_add_u32_e32 v194, 0, v58
	s_waitcnt lgkmcnt(0)
	v_mfma_f32_32x32x16_bf16 v[16:31], v[62:65], v[108:111], v[16:31]
	ds_read_b128 v[58:61], v194 offset:32768
	ds_read_b128 v[62:65], v194 offset:40960
	s_waitcnt lgkmcnt(1)
	v_mfma_f32_32x32x16_bf16 v[32:47], v[58:61], v[104:107], v[32:47]
	v_or_b32_e32 v58, 0xc0, v144
	v_bitop3_b32 v58, v58, v57, v50 bitop3:0xde
	v_add_u32_e32 v192, 0, v58
	s_waitcnt lgkmcnt(0)
	v_mfma_f32_32x32x16_bf16 v[16:31], v[62:65], v[104:107], v[16:31]
	ds_read_b128 v[58:61], v192 offset:32768
	ds_read_b128 v[62:65], v192 offset:40960
	s_waitcnt lgkmcnt(1)
	v_mfma_f32_32x32x16_bf16 v[32:47], v[58:61], v[100:103], v[32:47]
	v_or_b32_e32 v58, 0xe0, v144
	v_bitop3_b32 v57, v58, v57, v50 bitop3:0xde
	v_add_u32_e32 v190, 0, v57
	s_waitcnt lgkmcnt(0)
	v_mfma_f32_32x32x16_bf16 v[16:31], v[62:65], v[100:103], v[16:31]
	ds_read_b128 v[58:61], v190 offset:32768
	ds_read_b128 v[62:65], v190 offset:40960
	s_waitcnt lgkmcnt(1)
	v_mfma_f32_32x32x16_bf16 v[32:47], v[58:61], v[96:99], v[32:47]
	s_waitcnt lgkmcnt(0)
	v_mfma_f32_32x32x16_bf16 v[16:31], v[62:65], v[96:99], v[16:31]
	ds_read_b128 v[56:59], v199
	ds_read_b128 v[60:63], v199 offset:4096
	ds_read_b128 v[64:67], v182
	s_waitcnt lgkmcnt(0)
	v_mfma_f32_32x32x16_bf16 v[32:47], v[56:59], v[64:67], v[32:47]
	v_mfma_f32_32x32x16_bf16 v[16:31], v[60:63], v[64:67], v[16:31]
	ds_read_b128 v[56:59], v201
	ds_read_b128 v[60:63], v201 offset:4096
	ds_read_b128 v[64:67], v182 offset:1024
	s_waitcnt lgkmcnt(0)
	v_mfma_f32_32x32x16_bf16 v[32:47], v[56:59], v[64:67], v[32:47]
	v_mfma_f32_32x32x16_bf16 v[16:31], v[60:63], v[64:67], v[16:31]
	ds_read_b128 v[56:59], v203
	ds_read_b128 v[60:63], v203 offset:4096
	ds_read_b128 v[64:67], v182 offset:2048
	s_waitcnt lgkmcnt(0)
	v_mfma_f32_32x32x16_bf16 v[32:47], v[56:59], v[64:67], v[32:47]
	v_mfma_f32_32x32x16_bf16 v[16:31], v[60:63], v[64:67], v[16:31]
	ds_read_b128 v[56:59], v205
	ds_read_b128 v[60:63], v205 offset:4096
	ds_read_b128 v[64:67], v182 offset:3072
	s_waitcnt lgkmcnt(0)
	v_mfma_f32_32x32x16_bf16 v[32:47], v[56:59], v[64:67], v[32:47]
	v_mfma_f32_32x32x16_bf16 v[16:31], v[60:63], v[64:67], v[16:31]
	s_nop 10
	v_max_f32_e32 v56, v33, v33
	v_max_f32_e32 v57, v32, v32
	v_max_f32_e32 v56, v57, v56
	v_max3_f32 v56, v56, v34, v35
	v_max3_f32 v56, v56, v36, v37
	v_max3_f32 v56, v56, v38, v39
	v_max3_f32 v56, v56, v40, v41
	v_max3_f32 v56, v56, v42, v43
	v_max3_f32 v56, v56, v44, v45
	v_max3_f32 v56, v56, v46, v47
	v_max3_f32 v56, v56, v16, v17
	v_max3_f32 v56, v56, v18, v19
	v_max3_f32 v56, v56, v20, v21
	v_max3_f32 v56, v56, v22, v23
	v_max3_f32 v56, v56, v24, v25
	v_max3_f32 v56, v56, v26, v27
	v_max3_f32 v56, v56, v28, v29
	v_max3_f32 v56, v56, v30, v31
	v_mov_b32_e32 v57, v56
	s_nop 1
	v_permlane32_swap_b32_e32 v56, v57
	v_max_f32_e32 v57, v57, v57
	v_max_f32_e32 v56, v56, v56
	v_max_f32_e32 v56, v56, v57
	v_add_f32_e32 v57, 0x7149f2ca, v56
	v_max_f32_e32 v56, 0xf149f2ca, v56
	v_cmp_ge_f32_e32 vcc, s94, v57
	v_sub_f32_e32 v57, 0xf149f2ca, v56
	v_mul_f32_e32 v57, 0x3dd53b94, v57
	s_cmp_eq_u64 vcc, exec
	v_exp_f32_e32 v57, v57
	s_cselect_b64 vcc, -1, 0
	v_cndmask_b32_e32 v207, v56, v231, vcc
	v_mul_f32_e32 v56, 0xbdd53b94, v207
	v_cndmask_b32_e64 v206, v57, 1.0, vcc
	v_mov_b32_e32 v57, v56
	s_add_i32 s4, s46, 0x4040
	v_fmac_f32_e32 v57, 0x3dd53b94, v47
	s_ashr_i32 s5, s4, 31
	v_fma_f32 v140, v16, s76, v56
	v_fma_f32 v141, v17, s76, v56
	v_lshl_add_u64 v[16:17], v[162:163], 0, s[4:5]
	v_fmamk_f32 v32, v32, 0x3dd53b94, v56
	v_fmamk_f32 v33, v33, 0x3dd53b94, v56
	v_fma_f32 v132, v20, s76, v56
	v_fma_f32 v133, v21, s76, v56
	v_fma_f32 v138, v18, s76, v56
	v_fma_f32 v139, v19, s76, v56
	v_mul_lo_u32 v18, v17, s40
	v_mul_lo_u32 v19, v16, s41
	v_mad_u64_u32 v[16:17], s[10:11], v16, s40, 0
	v_lshl_add_u64 v[20:21], v[166:167], 0, s[4:5]
	v_fmamk_f32 v34, v34, 0x3dd53b94, v56
	v_fmamk_f32 v35, v35, 0x3dd53b94, v56
	v_fma_f32 v130, v22, s76, v56
	v_fma_f32 v131, v23, s76, v56
	v_exp_f32_e32 v159, v32
	v_exp_f32_e32 v161, v33
	v_add3_u32 v17, v17, v19, v18
	v_mul_lo_u32 v22, v21, s40
	v_mul_lo_u32 v23, v20, s41
	v_mad_u64_u32 v[20:21], s[10:11], v20, s40, 0
	v_lshl_add_u64 v[32:33], v[164:165], 0, s[4:5]
	v_fma_f32 v128, v24, s76, v56
	v_fma_f32 v129, v25, s76, v56
	v_exp_f32_e32 v157, v34
	v_exp_f32_e32 v160, v35
	v_lshlrev_b64 v[24:25], 1, v[16:17]
	v_add3_u32 v21, v21, v23, v22
	v_mad_u64_u32 v[34:35], s[4:5], v32, s3, v[52:53]
	v_fma_f32 v136, v28, s76, v56
	v_fma_f32 v137, v29, s76, v56
	v_lshl_add_u64 v[16:17], s[80:81], 0, v[24:25]
	v_lshlrev_b64 v[28:29], 1, v[20:21]
	v_mad_i32_i24 v35, v33, s3, v35
	v_lshl_add_u64 v[16:17], v[16:17], 0, v[48:49]
	v_lshl_add_u64 v[20:21], s[80:81], 0, v[28:29]
	v_lshl_add_u64 v[32:33], v[34:35], 0, v[50:51]
	global_load_dwordx4 v[16:19], v[16:17], off
	v_lshl_add_u64 v[20:21], v[20:21], 0, v[48:49]
	v_lshl_add_u64 v[24:25], s[78:79], 0, v[24:25]
	global_load_dwordx4 v[32:35], v[32:33], off
	v_lshl_add_u64 v[24:25], v[24:25], 0, v[48:49]
	global_load_dwordx4 v[20:23], v[20:21], off
	v_lshl_add_u64 v[28:29], s[78:79], 0, v[28:29]
	v_fma_f32 v142, v26, s76, v56
	v_fma_f32 v143, v27, s76, v56
	global_load_dwordx4 v[24:27], v[24:25], off
	v_lshl_add_u64 v[28:29], v[28:29], 0, v[48:49]
	v_fma_f32 v134, v30, s76, v56
	v_fma_f32 v135, v31, s76, v56
	global_load_dwordx4 v[28:31], v[28:29], off
	v_fmamk_f32 v36, v36, 0x3dd53b94, v56
	v_fmamk_f32 v37, v37, 0x3dd53b94, v56
	v_fmamk_f32 v38, v38, 0x3dd53b94, v56
	v_fmamk_f32 v39, v39, 0x3dd53b94, v56
	v_fmamk_f32 v40, v40, 0x3dd53b94, v56
	v_fmamk_f32 v41, v41, 0x3dd53b94, v56
	v_fmamk_f32 v42, v42, 0x3dd53b94, v56
	v_fmamk_f32 v43, v43, 0x3dd53b94, v56
	v_fmamk_f32 v44, v44, 0x3dd53b94, v56
	v_fmamk_f32 v45, v45, 0x3dd53b94, v56
	v_fmamk_f32 v46, v46, 0x3dd53b94, v56
	v_exp_f32_e32 v156, v36
	v_exp_f32_e32 v158, v37
	v_exp_f32_e32 v154, v38
	v_exp_f32_e32 v155, v39
	v_exp_f32_e32 v151, v40
	v_exp_f32_e32 v153, v41
	v_exp_f32_e32 v150, v42
	v_exp_f32_e32 v152, v43
	v_exp_f32_e32 v147, v44
	v_exp_f32_e32 v149, v45
	v_exp_f32_e32 v146, v46
	v_exp_f32_e32 v148, v57
	s_waitcnt vmcnt(0)
	s_addk_i32 s6, 0x4000
	s_waitcnt vmcnt(4)
	ds_write_b128 v185, v[16:19] offset:16384
	s_waitcnt vmcnt(2)
	ds_write_b128 v186, v[20:23] offset:16384
	s_waitcnt vmcnt(1)
	ds_write_b128 v187, v[24:27] offset:49152
	s_waitcnt vmcnt(0)
	ds_write_b128 v188, v[28:31] offset:49152
	ds_write_b128 v209, v[32:35]
	v_add_u32_e32 v184, s6, v54
	v_mov_b64_e32 v[62:63], v[14:15]
	v_mov_b64_e32 v[46:47], v[14:15]
	v_mov_b64_e32 v[30:31], v[14:15]
	v_cmp_gt_u32_e64 s[4:5], 32, v174
	s_addk_i32 s46, 0x4080
	s_addk_i32 s68, 0xff80
	v_mov_b64_e32 v[60:61], v[12:13]
	v_mov_b64_e32 v[58:59], v[10:11]
	v_mov_b64_e32 v[56:57], v[8:9]
	v_mov_b64_e32 v[54:55], v[6:7]
	v_mov_b64_e32 v[52:53], v[4:5]
	v_mov_b64_e32 v[50:51], v[2:3]
	v_mov_b64_e32 v[48:49], v[0:1]
	v_mov_b64_e32 v[44:45], v[12:13]
	v_mov_b64_e32 v[42:43], v[10:11]
	v_mov_b64_e32 v[40:41], v[8:9]
	v_mov_b64_e32 v[38:39], v[6:7]
	v_mov_b64_e32 v[36:37], v[4:5]
	v_mov_b64_e32 v[34:35], v[2:3]
	v_mov_b64_e32 v[32:33], v[0:1]
	v_mov_b64_e32 v[28:29], v[12:13]
	v_mov_b64_e32 v[26:27], v[10:11]
	v_mov_b64_e32 v[24:25], v[8:9]
	v_mov_b64_e32 v[22:23], v[6:7]
	v_mov_b64_e32 v[20:21], v[4:5]
	v_mov_b64_e32 v[18:19], v[2:3]
	v_mov_b64_e32 v[16:17], v[0:1]
	v_mul_lo_u32 v232, v163, s40
	v_mul_lo_u32 v233, v162, s41
	v_mad_u64_u32 v[234:235], s[100:101], v162, s40, 0
	v_add3_u32 v235, v235, v233, v232
	v_lshlrev_b64 v[234:235], 1, v[234:235]
	v_mul_lo_u32 v232, v167, s40
	v_mul_lo_u32 v233, v166, s41
	v_mad_u64_u32 v[236:237], s[100:101], v166, s40, 0
	v_add3_u32 v237, v237, v233, v232
	v_lshlrev_b64 v[236:237], 1, v[236:237]
	v_lshl_add_u64 v[162:163], v[168:169], 0, v[234:235]
	v_lshl_add_u64 v[166:167], v[168:169], 0, v[236:237]
	v_lshl_add_u64 v[168:169], v[170:171], 0, v[234:235]
	v_lshl_add_u64 v[170:171], v[170:171], 0, v[236:237]
	s_waitcnt lgkmcnt(0)
	s_barrier
.LBB0_762:
	ds_read_b128 v[64:67], v189 offset:49152
	ds_read_b128 v[68:71], v189 offset:57344
	ds_read_b128 v[236:239], v191 offset:49152
	ds_read_b128 v[240:243], v191 offset:57344
	ds_read_b128 v[244:247], v193 offset:49152
	ds_read_b128 v[248:251], v193 offset:57344
	s_add_i32 s9, s24, -1
	s_cmp_lt_u32 s9, 3
	s_cselect_b32 s100, s46, s68
	s_add_i32 s100, s100, s8
	s_ashr_i32 s101, s100, 31
	s_mul_hi_u32 s7, s100, s40
	s_mul_i32 s6, s100, s41
	s_add_u32 s7, s7, s6
	s_mul_i32 s6, s101, s40
	s_add_u32 s7, s7, s6
	s_mul_i32 s6, s100, s40
	s_lshl_b64 s[6:7], s[6:7], 1
	s_add_i32 s0, 0, 0x12800
	s_waitcnt lgkmcnt(5)
	v_mfma_f32_32x32x16_bf16 v[80:95], v[64:67], v[124:127], 0
	v_exp_f32_e32 v140, v140
	v_exp_f32_e32 v141, v141
	v_add_u32_e32 v211, s0, v198
	s_waitcnt lgkmcnt(4)
	v_mfma_f32_32x32x16_bf16 v[64:79], v[68:71], v[124:127], 0
	v_exp_f32_e32 v138, v138
	v_exp_f32_e32 v139, v139
	v_add_u32_e32 v210, s0, v200
	s_waitcnt lgkmcnt(3)
	v_mfma_f32_32x32x16_bf16 v[80:95], v[236:239], v[120:123], v[80:95]
	ds_read_b128 v[236:239], v195 offset:49152
	v_exp_f32_e32 v214, v130
	v_exp_f32_e32 v215, v131
	v_add_u32_e32 v216, s0, v202
	s_waitcnt lgkmcnt(3)
	v_mfma_f32_32x32x16_bf16 v[64:79], v[240:243], v[120:123], v[64:79]
	ds_read_b128 v[240:243], v195 offset:57344
	v_exp_f32_e32 v142, v142
	v_exp_f32_e32 v143, v143
	v_add_u32_e32 v217, s0, v204
	s_waitcnt lgkmcnt(3)
	v_mfma_f32_32x32x16_bf16 v[80:95], v[244:247], v[116:119], v[80:95]
	ds_read_b128 v[244:247], v196 offset:49152
	v_exp_f32_e32 v136, v136
	v_exp_f32_e32 v137, v137
	v_cvt_pk_bf16_f32 v130, v156, v158
	s_waitcnt lgkmcnt(3)
	v_mfma_f32_32x32x16_bf16 v[64:79], v[248:251], v[116:119], v[64:79]
	ds_read_b128 v[248:251], v196 offset:57344
	v_exp_f32_e32 v212, v132
	v_exp_f32_e32 v213, v133
	v_cvt_pk_bf16_f32 v131, v154, v155
	s_waitcnt lgkmcnt(3)
	v_mfma_f32_32x32x16_bf16 v[80:95], v[236:239], v[112:115], v[80:95]
	ds_read_b128 v[236:239], v194 offset:49152
	v_exp_f32_e32 v220, v128
	v_add_f32_e32 v128, 0, v159
	v_add_f32_e32 v128, v161, v128
	v_add_f32_e32 v128, v157, v128
	s_waitcnt lgkmcnt(3)
	v_mfma_f32_32x32x16_bf16 v[64:79], v[240:243], v[112:115], v[64:79]
	ds_read_b128 v[240:243], v194 offset:57344
	v_add_f32_e32 v128, v160, v128
	v_add_f32_e32 v128, v156, v128
	v_add_f32_e32 v128, v158, v128
	v_add_f32_e32 v128, v154, v128
	v_add_f32_e32 v128, v155, v128
	s_waitcnt lgkmcnt(3)
	v_mfma_f32_32x32x16_bf16 v[80:95], v[244:247], v[108:111], v[80:95]
	ds_read_b128 v[244:247], v192 offset:49152
	v_add_f32_e32 v128, v151, v128
	v_add_f32_e32 v128, v153, v128
	v_add_f32_e32 v128, v150, v128
	v_add_f32_e32 v128, v152, v128
	v_add_f32_e32 v128, v147, v128
	s_waitcnt lgkmcnt(3)
	v_mfma_f32_32x32x16_bf16 v[64:79], v[248:251], v[108:111], v[64:79]
	ds_read_b128 v[248:251], v192 offset:57344
	v_add_f32_e32 v128, v149, v128
	v_add_f32_e32 v128, v146, v128
	v_add_f32_e32 v128, v148, v128
	v_add_f32_e32 v128, v140, v128
	v_add_f32_e32 v128, v141, v128
	s_waitcnt lgkmcnt(3)
	v_mfma_f32_32x32x16_bf16 v[80:95], v[236:239], v[104:107], v[80:95]
	ds_read_b128 v[236:239], v190 offset:49152
	v_add_f32_e32 v128, v138, v128
	v_add_f32_e32 v128, v139, v128
	v_add_f32_e32 v128, v212, v128
	v_exp_f32_e32 v221, v129
	s_waitcnt lgkmcnt(3)
	v_mfma_f32_32x32x16_bf16 v[64:79], v[240:243], v[104:107], v[64:79]
	ds_read_b128 v[240:243], v190 offset:57344
	v_add_f32_e32 v128, v213, v128
	v_add_f32_e32 v128, v214, v128
	v_add_f32_e32 v128, v215, v128
	v_add_f32_e32 v128, v220, v128
	v_add_f32_e32 v128, v221, v128
	s_waitcnt lgkmcnt(3)
	v_mfma_f32_32x32x16_bf16 v[80:95], v[244:247], v[100:103], v[80:95]
	ds_read_b128 v[244:247], v211
	v_exp_f32_e32 v223, v134
	v_add_f32_e32 v128, v142, v128
	v_exp_f32_e32 v224, v135
	s_waitcnt lgkmcnt(3)
	v_mfma_f32_32x32x16_bf16 v[64:79], v[248:251], v[100:103], v[64:79]
	v_add_f32_e32 v128, v143, v128
	v_add_f32_e32 v128, v136, v128
	v_add_f32_e32 v128, v137, v128
	v_add_f32_e32 v128, v223, v128
	v_add_f32_e32 v218, v224, v128
	s_waitcnt lgkmcnt(2)
	v_mfma_f32_32x32x16_bf16 v[80:95], v[236:239], v[96:99], v[80:95]
	ds_read_b128 v[236:239], v211 offset:4096
	ds_read_b128 v[248:251], v182
	v_mov_b32_e32 v219, v218
	v_cvt_pk_bf16_f32 v128, v159, v161
	v_cvt_pk_bf16_f32 v129, v157, v160
	v_cvt_pk_bf16_f32 v132, v151, v153
	v_cvt_pk_bf16_f32 v133, v150, v152
	s_waitcnt lgkmcnt(3)
	v_mfma_f32_32x32x16_bf16 v[64:79], v[240:243], v[96:99], v[64:79]
	ds_read_b128 v[240:243], v210
	v_cvt_pk_bf16_f32 v134, v147, v149
	v_cvt_pk_bf16_f32 v135, v146, v148
	v_cvt_pk_bf16_f32 v154, v140, v141
	v_cvt_pk_bf16_f32 v155, v138, v139
	v_cvt_pk_bf16_f32 v156, v212, v213
	s_waitcnt lgkmcnt(1)
	v_mfma_f32_32x32x16_bf16 v[80:95], v[244:247], v[248:251], v[80:95]
	v_cvt_pk_bf16_f32 v157, v214, v215
	v_cvt_pk_bf16_f32 v220, v220, v221
	v_cvt_pk_bf16_f32 v221, v142, v143
	v_cvt_pk_bf16_f32 v222, v136, v137
	v_permlane32_swap_b32_e32 v218, v219
	v_mfma_f32_32x32x16_bf16 v[64:79], v[236:239], v[248:251], v[64:79]
	ds_read_b128 v[248:251], v210 offset:4096
	ds_read_b128 v[244:247], v182 offset:1024
	ds_read_b128 v[236:239], v216
	v_permlane32_swap_b32_e32 v128, v130
	v_cvt_pk_bf16_f32 v223, v223, v224
	v_permlane32_swap_b32_e32 v220, v222
	v_permlane32_swap_b32_e32 v129, v131
	v_permlane32_swap_b32_e32 v132, v134
	s_waitcnt lgkmcnt(1)
	v_mfma_f32_32x32x16_bf16 v[80:95], v[240:243], v[244:247], v[80:95]
	v_permlane32_swap_b32_e32 v133, v135
	v_permlane32_swap_b32_e32 v154, v156
	v_permlane32_swap_b32_e32 v155, v157
	v_permlane32_swap_b32_e32 v221, v223
	v_lshl_add_u64 v[136:137], s[6:7], 0, v[162:163]
	v_mfma_f32_32x32x16_bf16 v[64:79], v[248:251], v[244:247], v[64:79]
	ds_read_b128 v[244:247], v216 offset:4096
	ds_read_b128 v[240:243], v182 offset:2048
	ds_read_b128 v[248:251], v217
	v_lshl_add_u64 v[140:141], s[6:7], 0, v[166:167]
	v_lshl_add_u64 v[146:147], s[6:7], 0, v[168:169]
	v_lshl_add_u64 v[150:151], s[6:7], 0, v[170:171]
	v_lshl_add_u64 v[158:159], s[100:101], 0, v[164:165]
	v_mad_u64_u32 v[160:161], s[100:101], v158, s3, v[172:173]
	s_waitcnt lgkmcnt(1)
	v_mfma_f32_32x32x16_bf16 v[80:95], v[236:239], v[240:243], v[80:95]
	v_mad_i32_i24 v161, v159, s3, v161
	v_mfma_f32_32x32x16_bf16 v[64:79], v[244:247], v[240:243], v[64:79]
	ds_read_b128 v[240:243], v217 offset:4096
	ds_read_b128 v[236:239], v182 offset:3072
	ds_read_b64_tr_b16 v[224:225], v181 offset:0
	ds_read_b64_tr_b16 v[226:227], v181 offset:0x800
	ds_read_b64_tr_b16 v[232:233], v181 offset:0x1000
	ds_read_b64_tr_b16 v[234:235], v181 offset:0x1800
	s_waitcnt lgkmcnt(4)
	v_mfma_f32_32x32x16_bf16 v[80:95], v[248:251], v[236:239], v[80:95]
	v_mfma_f32_32x32x16_bf16 v[64:79], v[240:243], v[236:239], v[64:79]
	ds_read_b64_tr_b16 v[236:237], v181 offset:0x2000
	ds_read_b64_tr_b16 v[238:239], v181 offset:0x2800
	ds_read_b64_tr_b16 v[240:241], v181 offset:0x3000
	ds_read_b64_tr_b16 v[242:243], v181 offset:0x3800
	ds_read_b64_tr_b16 v[212:213], v181 offset:0x200
	ds_read_b64_tr_b16 v[214:215], v181 offset:0xa00
	global_load_dwordx4 v[136:139], v[136:137], off
	global_load_dwordx4 v[140:143], v[140:141], off
	global_load_dwordx4 v[146:149], v[146:147], off
	global_load_dwordx4 v[150:153], v[150:151], off
	global_load_dwordx4 v[158:161], v[160:161], off
	s_waitcnt lgkmcnt(8)
	v_mfma_f32_32x32x16_bf16 v[0:15], v[128:131], v[224:227], v[0:15]
	ds_read_b64_tr_b16 v[224:225], v181 offset:0x1200
	ds_read_b64_tr_b16 v[226:227], v181 offset:0x1a00
	v_max_f32_e32 v250, v81, v81
	v_max_f32_e32 v251, v80, v80
	v_max_f32_e32 v250, v251, v250
	v_max3_f32 v250, v250, v82, v83
	v_max3_f32 v250, v250, v84, v85
	s_waitcnt lgkmcnt(8)
	v_mfma_f32_32x32x16_bf16 v[0:15], v[132:135], v[232:235], v[0:15]
	ds_read_b64_tr_b16 v[232:233], v181 offset:0x2200
	ds_read_b64_tr_b16 v[234:235], v181 offset:0x2a00
	v_max3_f32 v250, v250, v86, v87
	v_max3_f32 v250, v250, v88, v89
	v_max3_f32 v250, v250, v90, v91
	v_max3_f32 v250, v250, v92, v93
	v_max3_f32 v250, v250, v94, v95
	s_waitcnt lgkmcnt(8)
	v_mfma_f32_32x32x16_bf16 v[0:15], v[154:157], v[236:239], v[0:15]
	ds_read_b64_tr_b16 v[236:237], v181 offset:0x3200
	ds_read_b64_tr_b16 v[238:239], v181 offset:0x3a00
	v_max3_f32 v250, v250, v64, v65
	v_max3_f32 v250, v250, v66, v67
	v_max3_f32 v250, v250, v68, v69
	v_max3_f32 v250, v250, v70, v71
	v_max3_f32 v250, v250, v72, v73
	s_waitcnt lgkmcnt(8)
	v_mfma_f32_32x32x16_bf16 v[0:15], v[220:223], v[240:243], v[0:15]
	ds_read_b64_tr_b16 v[240:241], v181 offset:0x400
	ds_read_b64_tr_b16 v[242:243], v181 offset:0xc00
	v_max3_f32 v250, v250, v74, v75
	v_max3_f32 v250, v250, v76, v77
	v_max3_f32 v250, v250, v78, v79
	v_mov_b32_e32 v251, v250
	s_nop 1
	v_permlane32_swap_b32_e32 v250, v251
	s_waitcnt lgkmcnt(8)
	v_mfma_f32_32x32x16_bf16 v[48:63], v[128:131], v[212:215], v[48:63]
	ds_read_b64_tr_b16 v[212:213], v181 offset:0x1400
	ds_read_b64_tr_b16 v[214:215], v181 offset:0x1c00
	v_max_f32_e32 v251, v251, v251
	v_max_f32_e32 v250, v250, v250
	v_max_f32_e32 v250, v250, v251
	v_sub_f32_e32 v251, v250, v207
	v_cmp_ge_f32_e32 vcc, s94, v251
	s_waitcnt lgkmcnt(8)
	v_mfma_f32_32x32x16_bf16 v[48:63], v[132:135], v[224:227], v[48:63]
	ds_read_b64_tr_b16 v[224:225], v181 offset:0x2400
	ds_read_b64_tr_b16 v[226:227], v181 offset:0x2c00
	v_max_f32_e32 v251, v207, v207
	v_max_f32_e32 v250, v251, v250
	v_sub_f32_e32 v251, v207, v250
	v_mul_f32_e32 v251, 0x3dd53b94, v251
	s_waitcnt lgkmcnt(8)
	v_mfma_f32_32x32x16_bf16 v[48:63], v[154:157], v[232:235], v[48:63]
	ds_read_b64_tr_b16 v[232:233], v181 offset:0x3400
	ds_read_b64_tr_b16 v[234:235], v181 offset:0x3c00
	v_exp_f32_e32 v251, v251
	s_waitcnt lgkmcnt(8)
	v_mfma_f32_32x32x16_bf16 v[48:63], v[220:223], v[236:239], v[48:63]
	ds_read_b64_tr_b16 v[236:237], v181 offset:0x600
	ds_read_b64_tr_b16 v[238:239], v181 offset:0xe00
	s_waitcnt lgkmcnt(8)
	v_mfma_f32_32x32x16_bf16 v[32:47], v[128:131], v[240:243], v[32:47]
	ds_read_b64_tr_b16 v[240:241], v181 offset:0x1600
	ds_read_b64_tr_b16 v[242:243], v181 offset:0x1e00
	s_waitcnt lgkmcnt(8)
	v_mfma_f32_32x32x16_bf16 v[32:47], v[132:135], v[212:215], v[32:47]
	ds_read_b64_tr_b16 v[212:213], v181 offset:0x2600
	ds_read_b64_tr_b16 v[214:215], v181 offset:0x2e00
	s_waitcnt lgkmcnt(8)
	v_mfma_f32_32x32x16_bf16 v[32:47], v[154:157], v[224:227], v[32:47]
	ds_read_b64_tr_b16 v[224:225], v181 offset:0x3600
	ds_read_b64_tr_b16 v[226:227], v181 offset:0x3e00
	s_waitcnt lgkmcnt(8)
	v_mfma_f32_32x32x16_bf16 v[32:47], v[220:223], v[232:235], v[32:47]
	s_waitcnt lgkmcnt(6)
	v_mfma_f32_32x32x16_bf16 v[16:31], v[128:131], v[236:239], v[16:31]
	s_waitcnt lgkmcnt(4)
	v_mfma_f32_32x32x16_bf16 v[16:31], v[132:135], v[240:243], v[16:31]
	s_waitcnt lgkmcnt(2)
	v_mfma_f32_32x32x16_bf16 v[16:31], v[154:157], v[212:215], v[16:31]
	s_waitcnt lgkmcnt(0)
	v_mfma_f32_32x32x16_bf16 v[16:31], v[220:223], v[224:227], v[16:31]
	s_cmp_eq_u64 vcc, exec
	s_cselect_b64 s[6:7], -1, 0
	s_barrier
	s_waitcnt vmcnt(0)
	v_cndmask_b32_e64 v220, v251, 1.0, s[6:7]
	v_add_u32_e32 v129, 0x10800, v208
	v_cmp_gt_f32_e32 vcc, 1.0, v220
	ds_write_b128 v187, v[146:149] offset:32768
	ds_write_b128 v188, v[150:153] offset:32768
	ds_write_b128 v129, v[158:161]
	ds_write_b128 v185, v[136:139]
	ds_write_b128 v186, v[140:143]
	s_nop 0
	s_nop 0
	s_nop 0
	s_nop 0
	s_nop 0
	s_cbranch_vccz .LBB0_766
	s_and_saveexec_b64 s[0:1], s[4:5]
	ds_write_b32 v183, v220 offset:128
	s_or_b64 exec, exec, s[0:1]
	s_waitcnt lgkmcnt(0)
	v_add_u32_e32 v129, v180, v144
	ds_read_b128 v[130:133], v129 offset:224
	ds_read_b128 v[134:137], v129 offset:192
	ds_read_b128 v[138:141], v129 offset:160
	ds_read_b128 v[146:149], v129 offset:128
	s_waitcnt lgkmcnt(3)
	v_pk_mul_f32 v[12:13], v[12:13], v[130:131]
	s_waitcnt lgkmcnt(2)
	v_pk_mul_f32 v[8:9], v[8:9], v[134:135]
	s_waitcnt lgkmcnt(1)
	v_pk_mul_f32 v[4:5], v[4:5], v[138:139]
	v_pk_mul_f32 v[14:15], v[14:15], v[132:133]
	v_pk_mul_f32 v[10:11], v[10:11], v[136:137]
	v_pk_mul_f32 v[6:7], v[6:7], v[140:141]
	s_waitcnt lgkmcnt(0)
	v_pk_mul_f32 v[2:3], v[2:3], v[148:149]
	v_pk_mul_f32 v[0:1], v[0:1], v[146:147]
	v_pk_mul_f32 v[60:61], v[60:61], v[130:131]
	v_pk_mul_f32 v[56:57], v[56:57], v[134:135]
	v_pk_mul_f32 v[52:53], v[52:53], v[138:139]
	v_pk_mul_f32 v[62:63], v[62:63], v[132:133]
	v_pk_mul_f32 v[58:59], v[58:59], v[136:137]
	v_pk_mul_f32 v[54:55], v[54:55], v[140:141]
	v_pk_mul_f32 v[50:51], v[50:51], v[148:149]
	v_pk_mul_f32 v[48:49], v[48:49], v[146:147]
	v_pk_mul_f32 v[44:45], v[44:45], v[130:131]
	v_pk_mul_f32 v[40:41], v[40:41], v[134:135]
	v_pk_mul_f32 v[36:37], v[36:37], v[138:139]
	v_pk_mul_f32 v[46:47], v[46:47], v[132:133]
	v_pk_mul_f32 v[42:43], v[42:43], v[136:137]
	v_pk_mul_f32 v[38:39], v[38:39], v[140:141]
	v_pk_mul_f32 v[34:35], v[34:35], v[148:149]
	v_pk_mul_f32 v[32:33], v[32:33], v[146:147]
	v_pk_mul_f32 v[28:29], v[28:29], v[130:131]
	v_pk_mul_f32 v[24:25], v[24:25], v[134:135]
	v_pk_mul_f32 v[20:21], v[20:21], v[138:139]
	v_pk_mul_f32 v[30:31], v[30:31], v[132:133]
	v_pk_mul_f32 v[26:27], v[26:27], v[136:137]
	v_pk_mul_f32 v[22:23], v[22:23], v[140:141]
	v_pk_mul_f32 v[18:19], v[18:19], v[148:149]
	v_pk_mul_f32 v[16:17], v[16:17], v[146:147]
.LBB0_766:
	v_cndmask_b32_e64 v207, v250, v207, s[6:7]
	v_mul_f32_e32 v146, 0xbdd53b94, v207
	v_fmamk_f32 v80, v80, 0x3dd53b94, v146
	v_exp_f32_e32 v128, v80
	v_fmamk_f32 v81, v81, 0x3dd53b94, v146
	v_fmamk_f32 v82, v82, 0x3dd53b94, v146
	v_fmamk_f32 v83, v83, 0x3dd53b94, v146
	v_fmamk_f32 v84, v84, 0x3dd53b94, v146
	v_fmamk_f32 v85, v85, 0x3dd53b94, v146
	v_fmamk_f32 v86, v86, 0x3dd53b94, v146
	v_fmamk_f32 v87, v87, 0x3dd53b94, v146
	v_fmamk_f32 v88, v88, 0x3dd53b94, v146
	v_fmamk_f32 v89, v89, 0x3dd53b94, v146
	v_fmamk_f32 v90, v90, 0x3dd53b94, v146
	v_fmamk_f32 v91, v91, 0x3dd53b94, v146
	v_fmamk_f32 v92, v92, 0x3dd53b94, v146
	v_fmamk_f32 v93, v93, 0x3dd53b94, v146
	v_fmamk_f32 v94, v94, 0x3dd53b94, v146
	v_fmamk_f32 v95, v95, 0x3dd53b94, v146
	v_fmamk_f32 v155, v64, 0x3dd53b94, v146
	v_fmamk_f32 v156, v65, 0x3dd53b94, v146
	v_fmamk_f32 v157, v66, 0x3dd53b94, v146
	v_fmamk_f32 v158, v67, 0x3dd53b94, v146
	v_fmamk_f32 v159, v68, 0x3dd53b94, v146
	v_fmamk_f32 v148, v69, 0x3dd53b94, v146
	v_fmamk_f32 v149, v70, 0x3dd53b94, v146
	v_fmamk_f32 v150, v71, 0x3dd53b94, v146
	v_fmamk_f32 v151, v72, 0x3dd53b94, v146
	v_fmamk_f32 v152, v73, 0x3dd53b94, v146
	v_fmamk_f32 v153, v74, 0x3dd53b94, v146
	v_fmamk_f32 v154, v75, 0x3dd53b94, v146
	v_fmamk_f32 v147, v76, 0x3dd53b94, v146
	v_exp_f32_e32 v143, v81
	v_exp_f32_e32 v129, v82
	v_exp_f32_e32 v142, v83
	v_exp_f32_e32 v130, v84
	v_exp_f32_e32 v141, v85
	v_exp_f32_e32 v131, v86
	v_exp_f32_e32 v140, v87
	v_exp_f32_e32 v132, v88
	v_exp_f32_e32 v139, v89
	v_exp_f32_e32 v133, v90
	v_exp_f32_e32 v138, v91
	v_exp_f32_e32 v134, v92
	v_exp_f32_e32 v137, v93
	v_exp_f32_e32 v135, v94
	v_exp_f32_e32 v136, v95
	v_fmamk_f32 v160, v77, 0x3dd53b94, v146
	v_fmamk_f32 v161, v78, 0x3dd53b94, v146
	v_fmac_f32_e32 v146, 0x3dd53b94, v79
	s_waitcnt lgkmcnt(2)
	s_barrier
	ds_read_b128 v[64:67], v189 offset:32768
	ds_read_b128 v[68:71], v189 offset:40960
	ds_read_b128 v[240:243], v191 offset:32768
	ds_read_b128 v[244:247], v191 offset:40960
	ds_read_b128 v[248:251], v193 offset:32768
	s_cmp_lt_u32 s9, 2
	s_cselect_b32 s100, s46, s68
	s_add_i32 s100, s100, s8
	s_add_i32 s100, s100, 64
	s_ashr_i32 s101, s100, 31
	s_mul_hi_u32 s7, s100, s40
	s_mul_i32 s6, s100, s41
	s_add_u32 s7, s7, s6
	s_mul_i32 s6, s101, s40
	s_add_u32 s7, s7, s6
	s_mul_i32 s6, s100, s40
	s_lshl_b64 s[6:7], s[6:7], 1
	s_waitcnt lgkmcnt(4)
	v_mfma_f32_32x32x16_bf16 v[80:95], v[64:67], v[124:127], 0
	v_exp_f32_e32 v212, v154
	v_add_f32_e32 v154, 0, v128
	v_add_f32_e32 v154, v143, v154
	v_add_f32_e32 v154, v129, v154
	s_waitcnt lgkmcnt(3)
	v_mfma_f32_32x32x16_bf16 v[64:79], v[68:71], v[124:127], 0
	v_add_f32_e32 v154, v142, v154
	v_add_f32_e32 v154, v130, v154
	v_add_f32_e32 v154, v141, v154
	v_add_f32_e32 v154, v131, v154
	v_add_f32_e32 v154, v140, v154
	s_waitcnt lgkmcnt(2)
	v_mfma_f32_32x32x16_bf16 v[80:95], v[240:243], v[120:123], v[80:95]
	ds_read_b128 v[240:243], v193 offset:40960
	v_add_f32_e32 v154, v132, v154
	v_add_f32_e32 v154, v139, v154
	v_add_f32_e32 v154, v133, v154
	v_add_f32_e32 v154, v138, v154
	v_add_f32_e32 v154, v134, v154
	s_waitcnt lgkmcnt(2)
	v_mfma_f32_32x32x16_bf16 v[64:79], v[244:247], v[120:123], v[64:79]
	ds_read_b128 v[244:247], v195 offset:32768
	v_exp_f32_e32 v155, v155
	v_exp_f32_e32 v156, v156
	v_add_f32_e32 v154, v137, v154
	s_waitcnt lgkmcnt(2)
	v_mfma_f32_32x32x16_bf16 v[80:95], v[248:251], v[116:119], v[80:95]
	ds_read_b128 v[248:251], v195 offset:40960
	v_exp_f32_e32 v157, v157
	v_add_f32_e32 v154, v135, v154
	v_exp_f32_e32 v158, v158
	s_waitcnt lgkmcnt(2)
	v_mfma_f32_32x32x16_bf16 v[64:79], v[240:243], v[116:119], v[64:79]
	ds_read_b128 v[240:243], v196 offset:32768
	v_add_f32_e32 v154, v136, v154
	v_exp_f32_e32 v159, v159
	v_add_f32_e32 v154, v155, v154
	v_add_f32_e32 v154, v156, v154
	s_waitcnt lgkmcnt(2)
	v_mfma_f32_32x32x16_bf16 v[80:95], v[244:247], v[112:115], v[80:95]
	ds_read_b128 v[244:247], v196 offset:40960
	v_exp_f32_e32 v148, v148
	v_exp_f32_e32 v149, v149
	v_add_f32_e32 v154, v157, v154
	s_waitcnt lgkmcnt(2)
	v_mfma_f32_32x32x16_bf16 v[64:79], v[248:251], v[112:115], v[64:79]
	ds_read_b128 v[248:251], v194 offset:32768
	v_exp_f32_e32 v150, v150
	v_add_f32_e32 v154, v158, v154
	v_exp_f32_e32 v151, v151
	s_waitcnt lgkmcnt(2)
	v_mfma_f32_32x32x16_bf16 v[80:95], v[240:243], v[108:111], v[80:95]
	ds_read_b128 v[240:243], v194 offset:40960
	v_add_f32_e32 v154, v159, v154
	v_exp_f32_e32 v152, v152
	v_add_f32_e32 v154, v148, v154
	v_add_f32_e32 v154, v149, v154
	s_waitcnt lgkmcnt(2)
	v_mfma_f32_32x32x16_bf16 v[64:79], v[244:247], v[108:111], v[64:79]
	ds_read_b128 v[244:247], v192 offset:32768
	v_exp_f32_e32 v153, v153
	v_add_f32_e32 v154, v150, v154
	v_exp_f32_e32 v147, v147
	s_waitcnt lgkmcnt(2)
	v_mfma_f32_32x32x16_bf16 v[80:95], v[248:251], v[104:107], v[80:95]
	ds_read_b128 v[248:251], v192 offset:40960
	v_add_f32_e32 v154, v151, v154
	v_exp_f32_e32 v160, v160
	v_add_f32_e32 v154, v152, v154
	v_add_f32_e32 v154, v153, v154
	s_waitcnt lgkmcnt(2)
	v_mfma_f32_32x32x16_bf16 v[64:79], v[240:243], v[104:107], v[64:79]
	ds_read_b128 v[240:243], v190 offset:32768
	v_exp_f32_e32 v161, v161
	v_exp_f32_e32 v146, v146
	v_add_f32_e32 v154, v212, v154
	s_waitcnt lgkmcnt(2)
	v_mfma_f32_32x32x16_bf16 v[80:95], v[244:247], v[100:103], v[80:95]
	ds_read_b128 v[244:247], v190 offset:40960
	v_add_f32_e32 v154, v147, v154
	v_add_f32_e32 v154, v160, v154
	v_add_f32_e32 v154, v161, v154
	v_cvt_pk_bf16_f32 v128, v128, v143
	v_cvt_pk_bf16_f32 v129, v129, v142
	s_waitcnt lgkmcnt(2)
	v_mfma_f32_32x32x16_bf16 v[64:79], v[248:251], v[100:103], v[64:79]
	ds_read_b128 v[248:251], v199
	v_cvt_pk_bf16_f32 v130, v130, v141
	v_cvt_pk_bf16_f32 v131, v131, v140
	v_cvt_pk_bf16_f32 v132, v132, v139
	v_cvt_pk_bf16_f32 v133, v133, v138
	v_add_f32_e32 v222, v146, v154
	s_waitcnt lgkmcnt(2)
	v_mfma_f32_32x32x16_bf16 v[80:95], v[240:243], v[96:99], v[80:95]
	v_mov_b32_e32 v223, v222
	s_nop 1
	v_permlane32_swap_b32_e32 v222, v223
	v_permlane32_swap_b32_e32 v128, v130
	v_cvt_pk_bf16_f32 v134, v134, v137
	v_cvt_pk_bf16_f32 v135, v135, v136
	s_waitcnt lgkmcnt(1)
	v_mfma_f32_32x32x16_bf16 v[64:79], v[244:247], v[96:99], v[64:79]
	ds_read_b128 v[244:247], v199 offset:4096
	ds_read_b128 v[240:243], v182
	v_cvt_pk_bf16_f32 v154, v155, v156
	v_cvt_pk_bf16_f32 v155, v157, v158
	v_cvt_pk_bf16_f32 v156, v159, v148
	v_cvt_pk_bf16_f32 v157, v149, v150
	v_cvt_pk_bf16_f32 v224, v151, v152
	s_waitcnt lgkmcnt(0)
	v_mfma_f32_32x32x16_bf16 v[80:95], v[248:251], v[240:243], v[80:95]
	ds_read_b128 v[248:251], v201
	v_cvt_pk_bf16_f32 v225, v153, v212
	v_cvt_pk_bf16_f32 v226, v147, v160
	v_cvt_pk_bf16_f32 v227, v161, v146
	v_permlane32_swap_b32_e32 v129, v131
	v_permlane32_swap_b32_e32 v132, v134
	v_mfma_f32_32x32x16_bf16 v[64:79], v[244:247], v[240:243], v[64:79]
	ds_read_b128 v[244:247], v201 offset:4096
	ds_read_b128 v[240:243], v182 offset:1024
	v_permlane32_swap_b32_e32 v133, v135
	v_permlane32_swap_b32_e32 v154, v156
	v_permlane32_swap_b32_e32 v155, v157
	v_permlane32_swap_b32_e32 v224, v226
	v_permlane32_swap_b32_e32 v225, v227
	s_waitcnt lgkmcnt(0)
	v_mfma_f32_32x32x16_bf16 v[80:95], v[248:251], v[240:243], v[80:95]
	ds_read_b128 v[248:251], v203
	v_lshl_add_u64 v[136:137], s[6:7], 0, v[162:163]
	v_lshl_add_u64 v[140:141], s[6:7], 0, v[166:167]
	v_lshl_add_u64 v[146:147], s[6:7], 0, v[168:169]
	v_lshl_add_u64 v[150:151], s[6:7], 0, v[170:171]
	v_lshl_add_u64 v[158:159], s[100:101], 0, v[164:165]
	v_mfma_f32_32x32x16_bf16 v[64:79], v[244:247], v[240:243], v[64:79]
	ds_read_b128 v[244:247], v203 offset:4096
	ds_read_b128 v[240:243], v182 offset:2048
	v_mad_u64_u32 v[160:161], s[100:101], v158, s3, v[172:173]
	v_mad_i32_i24 v161, v159, s3, v161
	s_waitcnt lgkmcnt(0)
	v_mfma_f32_32x32x16_bf16 v[80:95], v[248:251], v[240:243], v[80:95]
	ds_read_b128 v[248:251], v205
	v_mfma_f32_32x32x16_bf16 v[64:79], v[244:247], v[240:243], v[64:79]
	ds_read_b128 v[244:247], v205 offset:4096
	ds_read_b128 v[240:243], v182 offset:3072
	ds_read_b64_tr_b16 v[232:233], v184 offset:0
	ds_read_b64_tr_b16 v[234:235], v184 offset:0x800
	ds_read_b64_tr_b16 v[236:237], v184 offset:0x1000
	ds_read_b64_tr_b16 v[238:239], v184 offset:0x1800
	s_waitcnt lgkmcnt(4)
	v_mfma_f32_32x32x16_bf16 v[80:95], v[248:251], v[240:243], v[80:95]
	v_mfma_f32_32x32x16_bf16 v[64:79], v[244:247], v[240:243], v[64:79]
	ds_read_b64_tr_b16 v[240:241], v184 offset:0x2000
	ds_read_b64_tr_b16 v[242:243], v184 offset:0x2800
	ds_read_b64_tr_b16 v[244:245], v184 offset:0x3000
	ds_read_b64_tr_b16 v[246:247], v184 offset:0x3800
	global_load_dwordx4 v[136:139], v[136:137], off
	global_load_dwordx4 v[140:143], v[140:141], off
	global_load_dwordx4 v[146:149], v[146:147], off
	global_load_dwordx4 v[150:153], v[150:151], off
	global_load_dwordx4 v[158:161], v[160:161], off
	s_waitcnt lgkmcnt(6)
	v_mfma_f32_32x32x16_bf16 v[0:15], v[128:131], v[232:235], v[0:15]
	ds_read_b64_tr_b16 v[232:233], v184 offset:0x200
	ds_read_b64_tr_b16 v[234:235], v184 offset:0xa00
	s_waitcnt lgkmcnt(6)
	v_mfma_f32_32x32x16_bf16 v[0:15], v[132:135], v[236:239], v[0:15]
	ds_read_b64_tr_b16 v[236:237], v184 offset:0x1200
	ds_read_b64_tr_b16 v[238:239], v184 offset:0x1a00
	v_max_f32_e32 v250, v81, v81
	v_max_f32_e32 v251, v80, v80
	v_max_f32_e32 v250, v251, v250
	v_max3_f32 v250, v250, v82, v83
	v_max3_f32 v250, v250, v84, v85
	s_waitcnt lgkmcnt(6)
	v_mfma_f32_32x32x16_bf16 v[0:15], v[154:157], v[240:243], v[0:15]
	ds_read_b64_tr_b16 v[240:241], v184 offset:0x2200
	ds_read_b64_tr_b16 v[242:243], v184 offset:0x2a00
	v_max3_f32 v250, v250, v86, v87
	v_max3_f32 v250, v250, v88, v89
	v_max3_f32 v250, v250, v90, v91
	v_max3_f32 v250, v250, v92, v93
	v_max3_f32 v250, v250, v94, v95
	s_waitcnt lgkmcnt(6)
	v_mfma_f32_32x32x16_bf16 v[0:15], v[224:227], v[244:247], v[0:15]
	ds_read_b64_tr_b16 v[244:245], v184 offset:0x3200
	ds_read_b64_tr_b16 v[246:247], v184 offset:0x3a00
	v_max3_f32 v250, v250, v64, v65
	v_max3_f32 v250, v250, v66, v67
	v_max3_f32 v250, v250, v68, v69
	v_max3_f32 v250, v250, v70, v71
	v_max3_f32 v250, v250, v72, v73
	s_waitcnt lgkmcnt(6)
	v_mfma_f32_32x32x16_bf16 v[48:63], v[128:131], v[232:235], v[48:63]
	ds_read_b64_tr_b16 v[232:233], v184 offset:0x400
	ds_read_b64_tr_b16 v[234:235], v184 offset:0xc00
	v_max3_f32 v250, v250, v74, v75
	v_max3_f32 v250, v250, v76, v77
	v_max3_f32 v250, v250, v78, v79
	v_mov_b32_e32 v251, v250
	s_nop 1
	v_permlane32_swap_b32_e32 v250, v251
	s_waitcnt lgkmcnt(6)
	v_mfma_f32_32x32x16_bf16 v[48:63], v[132:135], v[236:239], v[48:63]
	ds_read_b64_tr_b16 v[236:237], v184 offset:0x1400
	ds_read_b64_tr_b16 v[238:239], v184 offset:0x1c00
	v_max_f32_e32 v251, v251, v251
	v_max_f32_e32 v250, v250, v250
	v_max_f32_e32 v250, v250, v251
	v_sub_f32_e32 v251, v250, v207
	v_cmp_ge_f32_e32 vcc, s94, v251
	s_waitcnt lgkmcnt(6)
	v_mfma_f32_32x32x16_bf16 v[48:63], v[154:157], v[240:243], v[48:63]
	ds_read_b64_tr_b16 v[240:241], v184 offset:0x2400
	ds_read_b64_tr_b16 v[242:243], v184 offset:0x2c00
	v_max_f32_e32 v251, v207, v207
	v_max_f32_e32 v250, v251, v250
	v_sub_f32_e32 v251, v207, v250
	v_mul_f32_e32 v251, 0x3dd53b94, v251
	s_waitcnt lgkmcnt(6)
	v_mfma_f32_32x32x16_bf16 v[48:63], v[224:227], v[244:247], v[48:63]
	ds_read_b64_tr_b16 v[244:245], v184 offset:0x3400
	ds_read_b64_tr_b16 v[246:247], v184 offset:0x3c00
	v_exp_f32_e32 v251, v251
	s_waitcnt lgkmcnt(6)
	v_mfma_f32_32x32x16_bf16 v[32:47], v[128:131], v[232:235], v[32:47]
	ds_read_b64_tr_b16 v[232:233], v184 offset:0x600
	ds_read_b64_tr_b16 v[234:235], v184 offset:0xe00
	s_waitcnt lgkmcnt(6)
	v_mfma_f32_32x32x16_bf16 v[32:47], v[132:135], v[236:239], v[32:47]
	ds_read_b64_tr_b16 v[236:237], v184 offset:0x1600
	ds_read_b64_tr_b16 v[238:239], v184 offset:0x1e00
	s_waitcnt lgkmcnt(6)
	v_mfma_f32_32x32x16_bf16 v[32:47], v[154:157], v[240:243], v[32:47]
	ds_read_b64_tr_b16 v[240:241], v184 offset:0x2600
	ds_read_b64_tr_b16 v[242:243], v184 offset:0x2e00
	s_waitcnt lgkmcnt(6)
	v_mfma_f32_32x32x16_bf16 v[32:47], v[224:227], v[244:247], v[32:47]
	ds_read_b64_tr_b16 v[244:245], v184 offset:0x3600
	ds_read_b64_tr_b16 v[246:247], v184 offset:0x3e00
	s_waitcnt lgkmcnt(6)
	v_mfma_f32_32x32x16_bf16 v[16:31], v[128:131], v[232:235], v[16:31]
	s_waitcnt lgkmcnt(4)
	v_mfma_f32_32x32x16_bf16 v[16:31], v[132:135], v[236:239], v[16:31]
	s_waitcnt lgkmcnt(2)
	v_mfma_f32_32x32x16_bf16 v[16:31], v[154:157], v[240:243], v[16:31]
	s_waitcnt lgkmcnt(0)
	v_mfma_f32_32x32x16_bf16 v[16:31], v[224:227], v[244:247], v[16:31]
	s_cmp_eq_u64 vcc, exec
	s_cselect_b64 s[6:7], -1, 0
	s_barrier
	s_waitcnt vmcnt(0)
	v_cndmask_b32_e64 v221, v251, 1.0, s[6:7]
	v_cmp_gt_f32_e32 vcc, 1.0, v221
	ds_write_b128 v187, v[146:149] offset:49152
	ds_write_b128 v188, v[150:153] offset:49152
	ds_write_b128 v209, v[158:161]
	ds_write_b128 v185, v[136:139] offset:16384
	ds_write_b128 v186, v[140:143] offset:16384
	s_nop 0
	s_nop 0
	s_nop 0
	s_nop 0
	s_nop 0
	s_cbranch_vccz .LBB0_770
	s_and_saveexec_b64 s[0:1], s[4:5]
	ds_write_b32 v183, v221 offset:128
	s_or_b64 exec, exec, s[0:1]
	s_waitcnt lgkmcnt(0)
	v_add_u32_e32 v129, v180, v144
	ds_read_b128 v[130:133], v129 offset:224
	ds_read_b128 v[134:137], v129 offset:192
	ds_read_b128 v[138:141], v129 offset:160
	ds_read_b128 v[146:149], v129 offset:128
	s_waitcnt lgkmcnt(3)
	v_pk_mul_f32 v[12:13], v[12:13], v[130:131]
	s_waitcnt lgkmcnt(2)
	v_pk_mul_f32 v[8:9], v[8:9], v[134:135]
	s_waitcnt lgkmcnt(1)
	v_pk_mul_f32 v[4:5], v[4:5], v[138:139]
	v_pk_mul_f32 v[14:15], v[14:15], v[132:133]
	v_pk_mul_f32 v[10:11], v[10:11], v[136:137]
	v_pk_mul_f32 v[6:7], v[6:7], v[140:141]
	s_waitcnt lgkmcnt(0)
	v_pk_mul_f32 v[2:3], v[2:3], v[148:149]
	v_pk_mul_f32 v[0:1], v[0:1], v[146:147]
	v_pk_mul_f32 v[60:61], v[60:61], v[130:131]
	v_pk_mul_f32 v[56:57], v[56:57], v[134:135]
	v_pk_mul_f32 v[52:53], v[52:53], v[138:139]
	v_pk_mul_f32 v[62:63], v[62:63], v[132:133]
	v_pk_mul_f32 v[58:59], v[58:59], v[136:137]
	v_pk_mul_f32 v[54:55], v[54:55], v[140:141]
	v_pk_mul_f32 v[50:51], v[50:51], v[148:149]
	v_pk_mul_f32 v[48:49], v[48:49], v[146:147]
	v_pk_mul_f32 v[44:45], v[44:45], v[130:131]
	v_pk_mul_f32 v[40:41], v[40:41], v[134:135]
	v_pk_mul_f32 v[36:37], v[36:37], v[138:139]
	v_pk_mul_f32 v[46:47], v[46:47], v[132:133]
	v_pk_mul_f32 v[42:43], v[42:43], v[136:137]
	v_pk_mul_f32 v[38:39], v[38:39], v[140:141]
	v_pk_mul_f32 v[34:35], v[34:35], v[148:149]
	v_pk_mul_f32 v[32:33], v[32:33], v[146:147]
	v_pk_mul_f32 v[28:29], v[28:29], v[130:131]
	v_pk_mul_f32 v[24:25], v[24:25], v[134:135]
	v_pk_mul_f32 v[20:21], v[20:21], v[138:139]
	v_pk_mul_f32 v[30:31], v[30:31], v[132:133]
	v_pk_mul_f32 v[26:27], v[26:27], v[136:137]
	v_pk_mul_f32 v[22:23], v[22:23], v[140:141]
	v_pk_mul_f32 v[18:19], v[18:19], v[148:149]
	v_pk_mul_f32 v[16:17], v[16:17], v[146:147]
